# s5_y/glu gemm_core: second A fragment of each K16 step in its own registers, its ds_read issued with the step's first reads (one exposed LDS latency per step instead of two)
# speedup vs baseline: 1.0204x; 1.0003x over previous
.LBB0_700:
	s_and_b32 s0, s12, 0xff
	s_mulk_i32 s0, 0xab
	s_lshr_b32 s0, s0, 11
	v_readlane_b32 s1, v255, 16
	s_add_i32 s2, s1, s0
	s_mul_i32 s0, s0, 12
	s_sub_i32 s3, s12, s0
	s_lshl_b32 s1, s3, 7
	s_lshl_b32 s0, s2, 9
	s_and_b32 s38, s1, 0x180
	s_or_b32 s0, s0, s38
	s_mulk_i32 s0, 0x600
	s_add_u32 s0, s70, s0
	s_addc_u32 s1, s71, 0
	s_mov_b64 s[22:23], s[0:1]
	s_lshl_b32 s3, s3, 5
	s_mul_i32 s10, s2, 0x180
	s_and_b32 s39, s3, 0x180
	s_add_i32 s10, s10, s39
	v_mov_b32_e32 v46, v235
	s_lshl_b32 s3, s10, 10
	s_add_u32 s40, s68, s3
	v_ashrrev_i32_e32 v32, 3, v46
	v_ashrrev_i32_e32 v33, 31, v32
	s_addc_u32 s41, s69, 0
	s_mov_b64 s[14:15], s[40:41]
	v_lshlrev_b64 v[0:1], 10, v[32:33]
	v_lshlrev_b32_e32 v47, 4, v46
	v_lshl_add_u64 v[0:1], s[40:41], 0, v[0:1]
	v_and_b32_e32 v192, 0x70, v47
	v_lshlrev_b32_e32 v230, 10, v32
	v_or_b32_e32 v230, v230, v192
	v_mul_u32_u24_e32 v231, 0x600, v32
	v_add_u32_e32 v231, v231, v192
	v_lshlrev_b32_e32 v232, 9, v32
	v_or_b32_e32 v232, v232, v192
	v_lshl_add_u64 v[128:129], v[0:1], 0, v[192:193]
	v_mov_b64_e32 v[0:1], s[0:1]
	v_mad_i64_i32 v[0:1], s[0:1], v32, s78, v[0:1]
	v_add_co_u32_e32 v34, vcc, s88, v128
	v_lshl_add_u64 v[130:131], v[0:1], 0, v[192:193]
	s_nop 0
	v_addc_co_u32_e32 v35, vcc, 0, v129, vcc
	v_add_co_u32_e32 v36, vcc, s8, v130
	v_addc_co_u32_e32 v37, vcc, 0, v131, vcc
	v_add_co_u32_e32 v38, vcc, s97, v128
	s_nop 0
	v_addc_co_u32_e32 v39, vcc, 0, v129, vcc
	v_add_co_u32_e32 v40, vcc, s76, v130
	s_nop 0
	v_addc_co_u32_e32 v41, vcc, 0, v131, vcc
	v_add_co_u32_e32 v42, vcc, s9, v130
	s_nop 0
	v_addc_co_u32_e32 v43, vcc, 0, v131, vcc
	v_add_co_u32_e32 v44, vcc, s76, v128
	s_nop 0
	v_addc_co_u32_e32 v45, vcc, 0, v129, vcc
	v_and_b32_e32 v48, 31, v46
	v_lshrrev_b32_e32 v51, 1, v46
	s_mov_b32 s0, 0x1ffffc0
	v_lshrrev_b32_e32 v49, 5, v46
	v_bfe_u32 v50, v46, 5, 1
	v_bfe_u32 v52, v46, 1, 3
	v_lshlrev_b32_e32 v53, 7, v46
	v_lshlrev_b32_e32 v54, 7, v32
	v_xor_b32_e32 v46, v47, v46
	v_and_or_b32 v47, v51, s0, v48
	s_movk_i32 s0, 0x70
	v_and_or_b32 v46, v46, s0, v54
	v_add_u32_e32 v134, s13, v46
	v_readlane_b32 s44, v253, 8
	s_lshl_b32 s0, s10, 9
	v_readlane_b32 s46, v253, 10
	v_readlane_b32 s47, v253, 11
	s_add_u32 s0, s46, s0
	v_lshlrev_b64 v[32:33], 9, v[32:33]
	s_addc_u32 s1, s47, 0
	s_mov_b64 s[80:81], s[0:1]
	v_and_b32_e32 v48, 0x2f80, v53
	v_lshl_add_u64 v[32:33], s[0:1], 0, v[32:33]
	s_mov_b32 s3, 0
	v_lshl_add_u64 v[132:133], v[32:33], 0, v[192:193]
	v_lshl_add_u32 v135, v47, 7, s13
	v_add_u32_e32 v136, s13, v48
	v_readlane_b32 s45, v253, 9
	v_readlane_b32 s48, v253, 12
	v_readlane_b32 s49, v253, 13
	v_readlane_b32 s50, v253, 14
	v_readlane_b32 s51, v253, 15
	v_bitop3_b32 v0, v49, v52, 1 bitop3:0x6c
	v_lshlrev_b32_e32 v137, 4, v0
	v_bitop3_b32 v0, v50, v52, 2 bitop3:0x36
	v_lshlrev_b32_e32 v138, 4, v0
	v_bitop3_b32 v0, v50, v52, 4 bitop3:0x36
	v_lshlrev_b32_e32 v139, 4, v0
	v_bitop3_b32 v0, v50, v52, 6 bitop3:0x36
	v_lshlrev_b32_e32 v140, 4, v0
	s_add_u32 s16, s14, 0x8000
	s_addc_u32 s17, s15, 0
	s_add_u32 s18, s14, 0x10000
	s_addc_u32 s19, s15, 0
	s_add_u32 s20, s14, 0x18000
	s_addc_u32 s21, s15, 0
	s_add_u32 s54, s22, 0xc000
	s_addc_u32 s55, s23, 0
	s_add_u32 s72, s22, 0x18000
	s_addc_u32 s73, s23, 0
	s_add_u32 s74, s22, 0x24000
	s_addc_u32 s75, s23, 0
	s_add_u32 s86, s80, 0x4000
	s_addc_u32 s87, s81, 0
	s_add_u32 s40, s80, 0x8000
	s_addc_u32 s41, s81, 0
	s_add_u32 s44, s80, 0xc000
	s_addc_u32 s45, s81, 0
	s_cmp_lg_u32 s13, 0
	s_cbranch_scc1 .Lsha_s5y_h1
	global_load_dwordx4 v[64:67], v230, s[14:15]
	global_load_dwordx4 v[68:71], v230, s[16:17]
	global_load_dwordx4 v[72:75], v230, s[18:19]
	global_load_dwordx4 v[76:79], v230, s[20:21]
	global_load_dwordx4 v[80:83], v231, s[22:23]
	global_load_dwordx4 v[84:87], v231, s[54:55]
	global_load_dwordx4 v[88:91], v231, s[72:73]
	global_load_dwordx4 v[92:95], v231, s[74:75]
	global_load_dwordx4 v[96:99], v230, s[14:15] offset:128
	global_load_dwordx4 v[100:103], v230, s[16:17] offset:128
	global_load_dwordx4 v[104:107], v230, s[18:19] offset:128
	global_load_dwordx4 v[108:111], v230, s[20:21] offset:128
	global_load_dwordx4 v[112:115], v231, s[22:23] offset:128
	global_load_dwordx4 v[116:119], v231, s[54:55] offset:128
	global_load_dwordx4 v[120:123], v231, s[72:73] offset:128
	global_load_dwordx4 v[124:127], v231, s[74:75] offset:128
	global_load_dwordx4 v[160:163], v230, s[14:15] offset:256
	global_load_dwordx4 v[164:167], v230, s[16:17] offset:256
	global_load_dwordx4 v[168:171], v230, s[18:19] offset:256
	global_load_dwordx4 v[172:175], v230, s[20:21] offset:256
	global_load_dwordx4 v[176:179], v231, s[22:23] offset:256
	global_load_dwordx4 v[180:183], v231, s[54:55] offset:256
	global_load_dwordx4 v[184:187], v231, s[72:73] offset:256
	global_load_dwordx4 v[188:191], v231, s[74:75] offset:256
	global_load_dwordx4 v[196:199], v230, s[14:15] offset:384
	global_load_dwordx4 v[200:203], v230, s[16:17] offset:384
	global_load_dwordx4 v[204:207], v230, s[18:19] offset:384
	global_load_dwordx4 v[208:211], v230, s[20:21] offset:384
	global_load_dwordx4 v[212:215], v231, s[22:23] offset:384
	global_load_dwordx4 v[216:219], v231, s[54:55] offset:384
	global_load_dwordx4 v[220:223], v231, s[72:73] offset:384
	global_load_dwordx4 v[224:227], v231, s[74:75] offset:384
	v_add_u32_e32 v128, v135, v137
	v_add_u32_e32 v132, v136, v137
	v_add_u32_e32 v129, v135, v138
	v_add_u32_e32 v133, v136, v138
	v_add_u32_e32 v130, v135, v139
	v_add_u32_e32 v228, v136, v139
	v_add_u32_e32 v131, v135, v140
	v_add_u32_e32 v229, v136, v140
	v_mov_b32_e32 v0, 0
	v_mov_b32_e32 v1, v0
	v_mov_b32_e32 v2, v0
	v_mov_b32_e32 v3, v0
	v_mov_b32_e32 v4, v0
	v_mov_b32_e32 v5, v0
	v_mov_b32_e32 v6, v0
	v_mov_b32_e32 v7, v0
	v_mov_b32_e32 v8, v0
	v_mov_b32_e32 v9, v0
	v_mov_b32_e32 v10, v0
	v_mov_b32_e32 v11, v0
	v_mov_b32_e32 v12, v0
	v_mov_b32_e32 v13, v0
	v_mov_b32_e32 v14, v0
	v_mov_b32_e32 v15, v0
	v_mov_b32_e32 v16, v0
	v_mov_b32_e32 v17, v0
	v_mov_b32_e32 v18, v0
	v_mov_b32_e32 v19, v0
	v_mov_b32_e32 v20, v0
	v_mov_b32_e32 v21, v0
	v_mov_b32_e32 v22, v0
	v_mov_b32_e32 v23, v0
	v_mov_b32_e32 v24, v0
	v_mov_b32_e32 v25, v0
	v_mov_b32_e32 v26, v0
	v_mov_b32_e32 v27, v0
	v_mov_b32_e32 v28, v0
	v_mov_b32_e32 v29, v0
	v_mov_b32_e32 v30, v0
	v_mov_b32_e32 v31, v0
	v_mov_b32_e32 v32, v0
	v_mov_b32_e32 v33, v0
	v_mov_b32_e32 v34, v0
	v_mov_b32_e32 v35, v0
	v_mov_b32_e32 v36, v0
	v_mov_b32_e32 v37, v0
	v_mov_b32_e32 v38, v0
	v_mov_b32_e32 v39, v0
	v_mov_b32_e32 v40, v0
	v_mov_b32_e32 v41, v0
	v_mov_b32_e32 v42, v0
	v_mov_b32_e32 v43, v0
	v_mov_b32_e32 v44, v0
	v_mov_b32_e32 v45, v0
	v_mov_b32_e32 v46, v0
	v_mov_b32_e32 v47, v0
	v_mov_b32_e32 v48, v0
	v_mov_b32_e32 v49, v0
	v_mov_b32_e32 v50, v0
	v_mov_b32_e32 v51, v0
	v_mov_b32_e32 v52, v0
	v_mov_b32_e32 v53, v0
	v_mov_b32_e32 v54, v0
	v_mov_b32_e32 v55, v0
	v_mov_b32_e32 v56, v0
	v_mov_b32_e32 v57, v0
	v_mov_b32_e32 v58, v0
	v_mov_b32_e32 v59, v0
	v_mov_b32_e32 v60, v0
	v_mov_b32_e32 v61, v0
	v_mov_b32_e32 v62, v0
	v_mov_b32_e32 v63, v0
	s_waitcnt vmcnt(24)
	ds_write_b128 v134, v[64:67]
	ds_write_b128 v134, v[80:83] offset:16384
	ds_write_b128 v134, v[68:71] offset:4096
	ds_write_b128 v134, v[84:87] offset:20480
	ds_write_b128 v134, v[72:75] offset:8192
	ds_write_b128 v134, v[88:91] offset:24576
	ds_write_b128 v134, v[76:79] offset:12288
	ds_write_b128 v134, v[92:95] offset:28672
	s_waitcnt lgkmcnt(0)
	s_barrier
	global_load_dwordx4 v[64:67], v230, s[14:15] offset:512
	global_load_dwordx4 v[68:71], v230, s[16:17] offset:512
	global_load_dwordx4 v[72:75], v230, s[18:19] offset:512
	global_load_dwordx4 v[76:79], v230, s[20:21] offset:512
	global_load_dwordx4 v[80:83], v231, s[22:23] offset:512
	global_load_dwordx4 v[84:87], v231, s[54:55] offset:512
	global_load_dwordx4 v[88:91], v231, s[72:73] offset:512
	global_load_dwordx4 v[92:95], v231, s[74:75] offset:512
	ds_read_b128 v[142:145], v128
	ds_read_b128 v[146:149], v132 offset:16384
	ds_read_b128 v[150:153], v132 offset:20480
	ds_read_b128 v[154:157], v128 offset:4096
	s_waitcnt lgkmcnt(2)
	v_mfma_f32_32x32x16_bf16 v[48:63], v[142:145], v[146:149], v[48:63]
	s_waitcnt lgkmcnt(1)
	v_mfma_f32_32x32x16_bf16 v[32:47], v[142:145], v[150:153], v[32:47]
	s_waitcnt lgkmcnt(0)
	v_mfma_f32_32x32x16_bf16 v[16:31], v[154:157], v[146:149], v[16:31]
	ds_read_b128 v[146:149], v133 offset:16384
	v_mfma_f32_32x32x16_bf16 v[0:15], v[154:157], v[150:153], v[0:15]
	ds_read_b128 v[142:145], v129
	ds_read_b128 v[150:153], v133 offset:20480
	ds_read_b128 v[154:157], v129 offset:4096
	s_waitcnt lgkmcnt(2)
	v_mfma_f32_32x32x16_bf16 v[48:63], v[142:145], v[146:149], v[48:63]
	s_waitcnt lgkmcnt(1)
	v_mfma_f32_32x32x16_bf16 v[32:47], v[142:145], v[150:153], v[32:47]
	s_waitcnt lgkmcnt(0)
	v_mfma_f32_32x32x16_bf16 v[16:31], v[154:157], v[146:149], v[16:31]
	ds_read_b128 v[146:149], v228 offset:16384
	v_mfma_f32_32x32x16_bf16 v[0:15], v[154:157], v[150:153], v[0:15]
	ds_read_b128 v[142:145], v130
	ds_read_b128 v[150:153], v228 offset:20480
	ds_read_b128 v[154:157], v130 offset:4096
	s_waitcnt lgkmcnt(2)
	v_mfma_f32_32x32x16_bf16 v[48:63], v[142:145], v[146:149], v[48:63]
	s_waitcnt lgkmcnt(1)
	v_mfma_f32_32x32x16_bf16 v[32:47], v[142:145], v[150:153], v[32:47]
	s_waitcnt lgkmcnt(0)
	v_mfma_f32_32x32x16_bf16 v[16:31], v[154:157], v[146:149], v[16:31]
	ds_read_b128 v[146:149], v229 offset:16384
	v_mfma_f32_32x32x16_bf16 v[0:15], v[154:157], v[150:153], v[0:15]
	ds_read_b128 v[142:145], v131
	ds_read_b128 v[150:153], v229 offset:20480
	ds_read_b128 v[154:157], v131 offset:4096
	s_waitcnt lgkmcnt(2)
	v_mfma_f32_32x32x16_bf16 v[48:63], v[142:145], v[146:149], v[48:63]
	s_waitcnt lgkmcnt(1)
	v_mfma_f32_32x32x16_bf16 v[32:47], v[142:145], v[150:153], v[32:47]
	s_waitcnt lgkmcnt(0)
	v_mfma_f32_32x32x16_bf16 v[16:31], v[154:157], v[146:149], v[16:31]
	v_mfma_f32_32x32x16_bf16 v[0:15], v[154:157], v[150:153], v[0:15]
	s_waitcnt vmcnt(24)
	ds_write_b128 v134, v[96:99] offset:32768
	ds_write_b128 v134, v[112:115] offset:49152
	ds_write_b128 v134, v[100:103] offset:36864
	ds_write_b128 v134, v[116:119] offset:53248
	ds_write_b128 v134, v[104:107] offset:40960
	ds_write_b128 v134, v[120:123] offset:57344
	ds_write_b128 v134, v[108:111] offset:45056
	ds_write_b128 v134, v[124:127] offset:61440
	s_waitcnt lgkmcnt(0)
	s_barrier
	global_load_dwordx4 v[96:99], v230, s[14:15] offset:640
	global_load_dwordx4 v[100:103], v230, s[16:17] offset:640
	global_load_dwordx4 v[104:107], v230, s[18:19] offset:640
	global_load_dwordx4 v[108:111], v230, s[20:21] offset:640
	global_load_dwordx4 v[112:115], v231, s[22:23] offset:640
	global_load_dwordx4 v[116:119], v231, s[54:55] offset:640
	global_load_dwordx4 v[120:123], v231, s[72:73] offset:640
	global_load_dwordx4 v[124:127], v231, s[74:75] offset:640
	ds_read_b128 v[142:145], v128 offset:32768
	ds_read_b128 v[146:149], v132 offset:49152
	ds_read_b128 v[150:153], v132 offset:53248
	ds_read_b128 v[154:157], v128 offset:36864
	s_waitcnt lgkmcnt(2)
	v_mfma_f32_32x32x16_bf16 v[48:63], v[142:145], v[146:149], v[48:63]
	s_waitcnt lgkmcnt(1)
	v_mfma_f32_32x32x16_bf16 v[32:47], v[142:145], v[150:153], v[32:47]
	s_waitcnt lgkmcnt(0)
	v_mfma_f32_32x32x16_bf16 v[16:31], v[154:157], v[146:149], v[16:31]
	ds_read_b128 v[146:149], v133 offset:49152
	v_mfma_f32_32x32x16_bf16 v[0:15], v[154:157], v[150:153], v[0:15]
	ds_read_b128 v[142:145], v129 offset:32768
	ds_read_b128 v[150:153], v133 offset:53248
	ds_read_b128 v[154:157], v129 offset:36864
	s_waitcnt lgkmcnt(2)
	v_mfma_f32_32x32x16_bf16 v[48:63], v[142:145], v[146:149], v[48:63]
	s_waitcnt lgkmcnt(1)
	v_mfma_f32_32x32x16_bf16 v[32:47], v[142:145], v[150:153], v[32:47]
	s_waitcnt lgkmcnt(0)
	v_mfma_f32_32x32x16_bf16 v[16:31], v[154:157], v[146:149], v[16:31]
	ds_read_b128 v[146:149], v228 offset:49152
	v_mfma_f32_32x32x16_bf16 v[0:15], v[154:157], v[150:153], v[0:15]
	ds_read_b128 v[142:145], v130 offset:32768
	ds_read_b128 v[150:153], v228 offset:53248
	ds_read_b128 v[154:157], v130 offset:36864
	s_waitcnt lgkmcnt(2)
	v_mfma_f32_32x32x16_bf16 v[48:63], v[142:145], v[146:149], v[48:63]
	s_waitcnt lgkmcnt(1)
	v_mfma_f32_32x32x16_bf16 v[32:47], v[142:145], v[150:153], v[32:47]
	s_waitcnt lgkmcnt(0)
	v_mfma_f32_32x32x16_bf16 v[16:31], v[154:157], v[146:149], v[16:31]
	ds_read_b128 v[146:149], v229 offset:49152
	v_mfma_f32_32x32x16_bf16 v[0:15], v[154:157], v[150:153], v[0:15]
	ds_read_b128 v[142:145], v131 offset:32768
	ds_read_b128 v[150:153], v229 offset:53248
	ds_read_b128 v[154:157], v131 offset:36864
	s_waitcnt lgkmcnt(2)
	v_mfma_f32_32x32x16_bf16 v[48:63], v[142:145], v[146:149], v[48:63]
	s_waitcnt lgkmcnt(1)
	v_mfma_f32_32x32x16_bf16 v[32:47], v[142:145], v[150:153], v[32:47]
	s_waitcnt lgkmcnt(0)
	v_mfma_f32_32x32x16_bf16 v[16:31], v[154:157], v[146:149], v[16:31]
	v_mfma_f32_32x32x16_bf16 v[0:15], v[154:157], v[150:153], v[0:15]
	s_waitcnt vmcnt(24)
	ds_write_b128 v134, v[160:163]
	ds_write_b128 v134, v[176:179] offset:16384
	ds_write_b128 v134, v[164:167] offset:4096
	ds_write_b128 v134, v[180:183] offset:20480
	ds_write_b128 v134, v[168:171] offset:8192
	ds_write_b128 v134, v[184:187] offset:24576
	ds_write_b128 v134, v[172:175] offset:12288
	ds_write_b128 v134, v[188:191] offset:28672
	s_waitcnt lgkmcnt(0)
	s_barrier
	global_load_dwordx4 v[160:163], v230, s[14:15] offset:768
	global_load_dwordx4 v[164:167], v230, s[16:17] offset:768
	global_load_dwordx4 v[168:171], v230, s[18:19] offset:768
	global_load_dwordx4 v[172:175], v230, s[20:21] offset:768
	global_load_dwordx4 v[176:179], v231, s[22:23] offset:768
	global_load_dwordx4 v[180:183], v231, s[54:55] offset:768
	global_load_dwordx4 v[184:187], v231, s[72:73] offset:768
	global_load_dwordx4 v[188:191], v231, s[74:75] offset:768
	ds_read_b128 v[142:145], v128
	ds_read_b128 v[146:149], v132 offset:16384
	ds_read_b128 v[150:153], v132 offset:20480
	ds_read_b128 v[154:157], v128 offset:4096
	s_waitcnt lgkmcnt(2)
	v_mfma_f32_32x32x16_bf16 v[48:63], v[142:145], v[146:149], v[48:63]
	s_waitcnt lgkmcnt(1)
	v_mfma_f32_32x32x16_bf16 v[32:47], v[142:145], v[150:153], v[32:47]
	s_waitcnt lgkmcnt(0)
	v_mfma_f32_32x32x16_bf16 v[16:31], v[154:157], v[146:149], v[16:31]
	ds_read_b128 v[146:149], v133 offset:16384
	v_mfma_f32_32x32x16_bf16 v[0:15], v[154:157], v[150:153], v[0:15]
	ds_read_b128 v[142:145], v129
	ds_read_b128 v[150:153], v133 offset:20480
	ds_read_b128 v[154:157], v129 offset:4096
	s_waitcnt lgkmcnt(2)
	v_mfma_f32_32x32x16_bf16 v[48:63], v[142:145], v[146:149], v[48:63]
	s_waitcnt lgkmcnt(1)
	v_mfma_f32_32x32x16_bf16 v[32:47], v[142:145], v[150:153], v[32:47]
	s_waitcnt lgkmcnt(0)
	v_mfma_f32_32x32x16_bf16 v[16:31], v[154:157], v[146:149], v[16:31]
	ds_read_b128 v[146:149], v228 offset:16384
	v_mfma_f32_32x32x16_bf16 v[0:15], v[154:157], v[150:153], v[0:15]
	ds_read_b128 v[142:145], v130
	ds_read_b128 v[150:153], v228 offset:20480
	ds_read_b128 v[154:157], v130 offset:4096
	s_waitcnt lgkmcnt(2)
	v_mfma_f32_32x32x16_bf16 v[48:63], v[142:145], v[146:149], v[48:63]
	s_waitcnt lgkmcnt(1)
	v_mfma_f32_32x32x16_bf16 v[32:47], v[142:145], v[150:153], v[32:47]
	s_waitcnt lgkmcnt(0)
	v_mfma_f32_32x32x16_bf16 v[16:31], v[154:157], v[146:149], v[16:31]
	ds_read_b128 v[146:149], v229 offset:16384
	v_mfma_f32_32x32x16_bf16 v[0:15], v[154:157], v[150:153], v[0:15]
	ds_read_b128 v[142:145], v131
	ds_read_b128 v[150:153], v229 offset:20480
	ds_read_b128 v[154:157], v131 offset:4096
	s_waitcnt lgkmcnt(2)
	v_mfma_f32_32x32x16_bf16 v[48:63], v[142:145], v[146:149], v[48:63]
	s_waitcnt lgkmcnt(1)
	v_mfma_f32_32x32x16_bf16 v[32:47], v[142:145], v[150:153], v[32:47]
	s_waitcnt lgkmcnt(0)
	v_mfma_f32_32x32x16_bf16 v[16:31], v[154:157], v[146:149], v[16:31]
	v_mfma_f32_32x32x16_bf16 v[0:15], v[154:157], v[150:153], v[0:15]
	s_waitcnt vmcnt(24)
	ds_write_b128 v134, v[196:199] offset:32768
	ds_write_b128 v134, v[212:215] offset:49152
	ds_write_b128 v134, v[200:203] offset:36864
	ds_write_b128 v134, v[216:219] offset:53248
	ds_write_b128 v134, v[204:207] offset:40960
	ds_write_b128 v134, v[220:223] offset:57344
	ds_write_b128 v134, v[208:211] offset:45056
	ds_write_b128 v134, v[224:227] offset:61440
	s_waitcnt lgkmcnt(0)
	s_barrier
	global_load_dwordx4 v[196:199], v230, s[14:15] offset:896
	global_load_dwordx4 v[200:203], v230, s[16:17] offset:896
	global_load_dwordx4 v[204:207], v230, s[18:19] offset:896
	global_load_dwordx4 v[208:211], v230, s[20:21] offset:896
	global_load_dwordx4 v[212:215], v231, s[22:23] offset:896
	global_load_dwordx4 v[216:219], v231, s[54:55] offset:896
	global_load_dwordx4 v[220:223], v231, s[72:73] offset:896
	global_load_dwordx4 v[224:227], v231, s[74:75] offset:896
	ds_read_b128 v[142:145], v128 offset:32768
	ds_read_b128 v[146:149], v132 offset:49152
	ds_read_b128 v[150:153], v132 offset:53248
	ds_read_b128 v[154:157], v128 offset:36864
	s_waitcnt lgkmcnt(2)
	v_mfma_f32_32x32x16_bf16 v[48:63], v[142:145], v[146:149], v[48:63]
	s_waitcnt lgkmcnt(1)
	v_mfma_f32_32x32x16_bf16 v[32:47], v[142:145], v[150:153], v[32:47]
	s_waitcnt lgkmcnt(0)
	v_mfma_f32_32x32x16_bf16 v[16:31], v[154:157], v[146:149], v[16:31]
	ds_read_b128 v[146:149], v133 offset:49152
	v_mfma_f32_32x32x16_bf16 v[0:15], v[154:157], v[150:153], v[0:15]
	ds_read_b128 v[142:145], v129 offset:32768
	ds_read_b128 v[150:153], v133 offset:53248
	ds_read_b128 v[154:157], v129 offset:36864
	s_waitcnt lgkmcnt(2)
	v_mfma_f32_32x32x16_bf16 v[48:63], v[142:145], v[146:149], v[48:63]
	s_waitcnt lgkmcnt(1)
	v_mfma_f32_32x32x16_bf16 v[32:47], v[142:145], v[150:153], v[32:47]
	s_waitcnt lgkmcnt(0)
	v_mfma_f32_32x32x16_bf16 v[16:31], v[154:157], v[146:149], v[16:31]
	ds_read_b128 v[146:149], v228 offset:49152
	v_mfma_f32_32x32x16_bf16 v[0:15], v[154:157], v[150:153], v[0:15]
	ds_read_b128 v[142:145], v130 offset:32768
	ds_read_b128 v[150:153], v228 offset:53248
	ds_read_b128 v[154:157], v130 offset:36864
	s_waitcnt lgkmcnt(2)
	v_mfma_f32_32x32x16_bf16 v[48:63], v[142:145], v[146:149], v[48:63]
	s_waitcnt lgkmcnt(1)
	v_mfma_f32_32x32x16_bf16 v[32:47], v[142:145], v[150:153], v[32:47]
	s_waitcnt lgkmcnt(0)
	v_mfma_f32_32x32x16_bf16 v[16:31], v[154:157], v[146:149], v[16:31]
	ds_read_b128 v[146:149], v229 offset:49152
	v_mfma_f32_32x32x16_bf16 v[0:15], v[154:157], v[150:153], v[0:15]
	ds_read_b128 v[142:145], v131 offset:32768
	ds_read_b128 v[150:153], v229 offset:53248
	ds_read_b128 v[154:157], v131 offset:36864
	s_waitcnt lgkmcnt(2)
	v_mfma_f32_32x32x16_bf16 v[48:63], v[142:145], v[146:149], v[48:63]
	s_waitcnt lgkmcnt(1)
	v_mfma_f32_32x32x16_bf16 v[32:47], v[142:145], v[150:153], v[32:47]
	s_waitcnt lgkmcnt(0)
	v_mfma_f32_32x32x16_bf16 v[16:31], v[154:157], v[146:149], v[16:31]
	v_mfma_f32_32x32x16_bf16 v[0:15], v[154:157], v[150:153], v[0:15]
	s_waitcnt vmcnt(24)
	ds_write_b128 v134, v[64:67]
	ds_write_b128 v134, v[80:83] offset:16384
	ds_write_b128 v134, v[68:71] offset:4096
	ds_write_b128 v134, v[84:87] offset:20480
	ds_write_b128 v134, v[72:75] offset:8192
	ds_write_b128 v134, v[88:91] offset:24576
	ds_write_b128 v134, v[76:79] offset:12288
	ds_write_b128 v134, v[92:95] offset:28672
	s_waitcnt lgkmcnt(0)
	s_barrier
	global_load_dwordx4 v[64:67], v232, s[80:81]
	global_load_dwordx4 v[68:71], v232, s[86:87]
	global_load_dwordx4 v[72:75], v232, s[40:41]
	global_load_dwordx4 v[76:79], v232, s[44:45]
	global_load_dwordx4 v[80:83], v231, s[22:23] offset:1024
	global_load_dwordx4 v[84:87], v231, s[54:55] offset:1024
	global_load_dwordx4 v[88:91], v231, s[72:73] offset:1024
	global_load_dwordx4 v[92:95], v231, s[74:75] offset:1024
	ds_read_b128 v[142:145], v128
	ds_read_b128 v[146:149], v132 offset:16384
	ds_read_b128 v[150:153], v132 offset:20480
	ds_read_b128 v[154:157], v128 offset:4096
	s_waitcnt lgkmcnt(2)
	v_mfma_f32_32x32x16_bf16 v[48:63], v[142:145], v[146:149], v[48:63]
	s_waitcnt lgkmcnt(1)
	v_mfma_f32_32x32x16_bf16 v[32:47], v[142:145], v[150:153], v[32:47]
	s_waitcnt lgkmcnt(0)
	v_mfma_f32_32x32x16_bf16 v[16:31], v[154:157], v[146:149], v[16:31]
	ds_read_b128 v[146:149], v133 offset:16384
	v_mfma_f32_32x32x16_bf16 v[0:15], v[154:157], v[150:153], v[0:15]
	ds_read_b128 v[142:145], v129
	ds_read_b128 v[150:153], v133 offset:20480
	ds_read_b128 v[154:157], v129 offset:4096
	s_waitcnt lgkmcnt(2)
	v_mfma_f32_32x32x16_bf16 v[48:63], v[142:145], v[146:149], v[48:63]
	s_waitcnt lgkmcnt(1)
	v_mfma_f32_32x32x16_bf16 v[32:47], v[142:145], v[150:153], v[32:47]
	s_waitcnt lgkmcnt(0)
	v_mfma_f32_32x32x16_bf16 v[16:31], v[154:157], v[146:149], v[16:31]
	ds_read_b128 v[146:149], v228 offset:16384
	v_mfma_f32_32x32x16_bf16 v[0:15], v[154:157], v[150:153], v[0:15]
	ds_read_b128 v[142:145], v130
	ds_read_b128 v[150:153], v228 offset:20480
	ds_read_b128 v[154:157], v130 offset:4096
	s_waitcnt lgkmcnt(2)
	v_mfma_f32_32x32x16_bf16 v[48:63], v[142:145], v[146:149], v[48:63]
	s_waitcnt lgkmcnt(1)
	v_mfma_f32_32x32x16_bf16 v[32:47], v[142:145], v[150:153], v[32:47]
	s_waitcnt lgkmcnt(0)
	v_mfma_f32_32x32x16_bf16 v[16:31], v[154:157], v[146:149], v[16:31]
	ds_read_b128 v[146:149], v229 offset:16384
	v_mfma_f32_32x32x16_bf16 v[0:15], v[154:157], v[150:153], v[0:15]
	ds_read_b128 v[142:145], v131
	ds_read_b128 v[150:153], v229 offset:20480
	ds_read_b128 v[154:157], v131 offset:4096
	s_waitcnt lgkmcnt(2)
	v_mfma_f32_32x32x16_bf16 v[48:63], v[142:145], v[146:149], v[48:63]
	s_waitcnt lgkmcnt(1)
	v_mfma_f32_32x32x16_bf16 v[32:47], v[142:145], v[150:153], v[32:47]
	s_waitcnt lgkmcnt(0)
	v_mfma_f32_32x32x16_bf16 v[16:31], v[154:157], v[146:149], v[16:31]
	v_mfma_f32_32x32x16_bf16 v[0:15], v[154:157], v[150:153], v[0:15]
	s_waitcnt vmcnt(24)
	ds_write_b128 v134, v[96:99] offset:32768
	ds_write_b128 v134, v[112:115] offset:49152
	ds_write_b128 v134, v[100:103] offset:36864
	ds_write_b128 v134, v[116:119] offset:53248
	ds_write_b128 v134, v[104:107] offset:40960
	ds_write_b128 v134, v[120:123] offset:57344
	ds_write_b128 v134, v[108:111] offset:45056
	ds_write_b128 v134, v[124:127] offset:61440
	s_waitcnt lgkmcnt(0)
	s_barrier
	global_load_dwordx4 v[96:99], v232, s[80:81] offset:128
	global_load_dwordx4 v[100:103], v232, s[86:87] offset:128
	global_load_dwordx4 v[104:107], v232, s[40:41] offset:128
	global_load_dwordx4 v[108:111], v232, s[44:45] offset:128
	global_load_dwordx4 v[112:115], v231, s[22:23] offset:1152
	global_load_dwordx4 v[116:119], v231, s[54:55] offset:1152
	global_load_dwordx4 v[120:123], v231, s[72:73] offset:1152
	global_load_dwordx4 v[124:127], v231, s[74:75] offset:1152
	ds_read_b128 v[142:145], v128 offset:32768
	ds_read_b128 v[146:149], v132 offset:49152
	ds_read_b128 v[150:153], v132 offset:53248
	ds_read_b128 v[154:157], v128 offset:36864
	s_waitcnt lgkmcnt(2)
	v_mfma_f32_32x32x16_bf16 v[48:63], v[142:145], v[146:149], v[48:63]
	s_waitcnt lgkmcnt(1)
	v_mfma_f32_32x32x16_bf16 v[32:47], v[142:145], v[150:153], v[32:47]
	s_waitcnt lgkmcnt(0)
	v_mfma_f32_32x32x16_bf16 v[16:31], v[154:157], v[146:149], v[16:31]
	ds_read_b128 v[146:149], v133 offset:49152
	v_mfma_f32_32x32x16_bf16 v[0:15], v[154:157], v[150:153], v[0:15]
	ds_read_b128 v[142:145], v129 offset:32768
	ds_read_b128 v[150:153], v133 offset:53248
	ds_read_b128 v[154:157], v129 offset:36864
	s_waitcnt lgkmcnt(2)
	v_mfma_f32_32x32x16_bf16 v[48:63], v[142:145], v[146:149], v[48:63]
	s_waitcnt lgkmcnt(1)
	v_mfma_f32_32x32x16_bf16 v[32:47], v[142:145], v[150:153], v[32:47]
	s_waitcnt lgkmcnt(0)
	v_mfma_f32_32x32x16_bf16 v[16:31], v[154:157], v[146:149], v[16:31]
	ds_read_b128 v[146:149], v228 offset:49152
	v_mfma_f32_32x32x16_bf16 v[0:15], v[154:157], v[150:153], v[0:15]
	ds_read_b128 v[142:145], v130 offset:32768
	ds_read_b128 v[150:153], v228 offset:53248
	ds_read_b128 v[154:157], v130 offset:36864
	s_waitcnt lgkmcnt(2)
	v_mfma_f32_32x32x16_bf16 v[48:63], v[142:145], v[146:149], v[48:63]
	s_waitcnt lgkmcnt(1)
	v_mfma_f32_32x32x16_bf16 v[32:47], v[142:145], v[150:153], v[32:47]
	s_waitcnt lgkmcnt(0)
	v_mfma_f32_32x32x16_bf16 v[16:31], v[154:157], v[146:149], v[16:31]
	ds_read_b128 v[146:149], v229 offset:49152
	v_mfma_f32_32x32x16_bf16 v[0:15], v[154:157], v[150:153], v[0:15]
	ds_read_b128 v[142:145], v131 offset:32768
	ds_read_b128 v[150:153], v229 offset:53248
	ds_read_b128 v[154:157], v131 offset:36864
	s_waitcnt lgkmcnt(2)
	v_mfma_f32_32x32x16_bf16 v[48:63], v[142:145], v[146:149], v[48:63]
	s_waitcnt lgkmcnt(1)
	v_mfma_f32_32x32x16_bf16 v[32:47], v[142:145], v[150:153], v[32:47]
	s_waitcnt lgkmcnt(0)
	v_mfma_f32_32x32x16_bf16 v[16:31], v[154:157], v[146:149], v[16:31]
	v_mfma_f32_32x32x16_bf16 v[0:15], v[154:157], v[150:153], v[0:15]
	s_waitcnt vmcnt(24)
	ds_write_b128 v134, v[160:163]
	ds_write_b128 v134, v[176:179] offset:16384
	ds_write_b128 v134, v[164:167] offset:4096
	ds_write_b128 v134, v[180:183] offset:20480
	ds_write_b128 v134, v[168:171] offset:8192
	ds_write_b128 v134, v[184:187] offset:24576
	ds_write_b128 v134, v[172:175] offset:12288
	ds_write_b128 v134, v[188:191] offset:28672
	s_waitcnt lgkmcnt(0)
	s_barrier
	global_load_dwordx4 v[160:163], v232, s[80:81] offset:256
	global_load_dwordx4 v[164:167], v232, s[86:87] offset:256
	global_load_dwordx4 v[168:171], v232, s[40:41] offset:256
	global_load_dwordx4 v[172:175], v232, s[44:45] offset:256
	global_load_dwordx4 v[176:179], v231, s[22:23] offset:1280
	global_load_dwordx4 v[180:183], v231, s[54:55] offset:1280
	global_load_dwordx4 v[184:187], v231, s[72:73] offset:1280
	global_load_dwordx4 v[188:191], v231, s[74:75] offset:1280
	ds_read_b128 v[142:145], v128
	ds_read_b128 v[146:149], v132 offset:16384
	ds_read_b128 v[150:153], v132 offset:20480
	ds_read_b128 v[154:157], v128 offset:4096
	s_waitcnt lgkmcnt(2)
	v_mfma_f32_32x32x16_bf16 v[48:63], v[142:145], v[146:149], v[48:63]
	s_waitcnt lgkmcnt(1)
	v_mfma_f32_32x32x16_bf16 v[32:47], v[142:145], v[150:153], v[32:47]
	s_waitcnt lgkmcnt(0)
	v_mfma_f32_32x32x16_bf16 v[16:31], v[154:157], v[146:149], v[16:31]
	ds_read_b128 v[146:149], v133 offset:16384
	v_mfma_f32_32x32x16_bf16 v[0:15], v[154:157], v[150:153], v[0:15]
	ds_read_b128 v[142:145], v129
	ds_read_b128 v[150:153], v133 offset:20480
	ds_read_b128 v[154:157], v129 offset:4096
	s_waitcnt lgkmcnt(2)
	v_mfma_f32_32x32x16_bf16 v[48:63], v[142:145], v[146:149], v[48:63]
	s_waitcnt lgkmcnt(1)
	v_mfma_f32_32x32x16_bf16 v[32:47], v[142:145], v[150:153], v[32:47]
	s_waitcnt lgkmcnt(0)
	v_mfma_f32_32x32x16_bf16 v[16:31], v[154:157], v[146:149], v[16:31]
	ds_read_b128 v[146:149], v228 offset:16384
	v_mfma_f32_32x32x16_bf16 v[0:15], v[154:157], v[150:153], v[0:15]
	ds_read_b128 v[142:145], v130
	ds_read_b128 v[150:153], v228 offset:20480
	ds_read_b128 v[154:157], v130 offset:4096
	s_waitcnt lgkmcnt(2)
	v_mfma_f32_32x32x16_bf16 v[48:63], v[142:145], v[146:149], v[48:63]
	s_waitcnt lgkmcnt(1)
	v_mfma_f32_32x32x16_bf16 v[32:47], v[142:145], v[150:153], v[32:47]
	s_waitcnt lgkmcnt(0)
	v_mfma_f32_32x32x16_bf16 v[16:31], v[154:157], v[146:149], v[16:31]
	ds_read_b128 v[146:149], v229 offset:16384
	v_mfma_f32_32x32x16_bf16 v[0:15], v[154:157], v[150:153], v[0:15]
	ds_read_b128 v[142:145], v131
	ds_read_b128 v[150:153], v229 offset:20480
	ds_read_b128 v[154:157], v131 offset:4096
	s_waitcnt lgkmcnt(2)
	v_mfma_f32_32x32x16_bf16 v[48:63], v[142:145], v[146:149], v[48:63]
	s_waitcnt lgkmcnt(1)
	v_mfma_f32_32x32x16_bf16 v[32:47], v[142:145], v[150:153], v[32:47]
	s_waitcnt lgkmcnt(0)
	v_mfma_f32_32x32x16_bf16 v[16:31], v[154:157], v[146:149], v[16:31]
	v_mfma_f32_32x32x16_bf16 v[0:15], v[154:157], v[150:153], v[0:15]
	s_waitcnt vmcnt(24)
	ds_write_b128 v134, v[196:199] offset:32768
	ds_write_b128 v134, v[212:215] offset:49152
	ds_write_b128 v134, v[200:203] offset:36864
	ds_write_b128 v134, v[216:219] offset:53248
	ds_write_b128 v134, v[204:207] offset:40960
	ds_write_b128 v134, v[220:223] offset:57344
	ds_write_b128 v134, v[208:211] offset:45056
	ds_write_b128 v134, v[224:227] offset:61440
	s_waitcnt lgkmcnt(0)
	s_barrier
	global_load_dwordx4 v[196:199], v232, s[80:81] offset:384
	global_load_dwordx4 v[200:203], v232, s[86:87] offset:384
	global_load_dwordx4 v[204:207], v232, s[40:41] offset:384
	global_load_dwordx4 v[208:211], v232, s[44:45] offset:384
	global_load_dwordx4 v[212:215], v231, s[22:23] offset:1408
	global_load_dwordx4 v[216:219], v231, s[54:55] offset:1408
	global_load_dwordx4 v[220:223], v231, s[72:73] offset:1408
	global_load_dwordx4 v[224:227], v231, s[74:75] offset:1408
	ds_read_b128 v[142:145], v128 offset:32768
	ds_read_b128 v[146:149], v132 offset:49152
	ds_read_b128 v[150:153], v132 offset:53248
	ds_read_b128 v[154:157], v128 offset:36864
	s_waitcnt lgkmcnt(2)
	v_mfma_f32_32x32x16_bf16 v[48:63], v[142:145], v[146:149], v[48:63]
	s_waitcnt lgkmcnt(1)
	v_mfma_f32_32x32x16_bf16 v[32:47], v[142:145], v[150:153], v[32:47]
	s_waitcnt lgkmcnt(0)
	v_mfma_f32_32x32x16_bf16 v[16:31], v[154:157], v[146:149], v[16:31]
	ds_read_b128 v[146:149], v133 offset:49152
	v_mfma_f32_32x32x16_bf16 v[0:15], v[154:157], v[150:153], v[0:15]
	ds_read_b128 v[142:145], v129 offset:32768
	ds_read_b128 v[150:153], v133 offset:53248
	ds_read_b128 v[154:157], v129 offset:36864
	s_waitcnt lgkmcnt(2)
	v_mfma_f32_32x32x16_bf16 v[48:63], v[142:145], v[146:149], v[48:63]
	s_waitcnt lgkmcnt(1)
	v_mfma_f32_32x32x16_bf16 v[32:47], v[142:145], v[150:153], v[32:47]
	s_waitcnt lgkmcnt(0)
	v_mfma_f32_32x32x16_bf16 v[16:31], v[154:157], v[146:149], v[16:31]
	ds_read_b128 v[146:149], v228 offset:49152
	v_mfma_f32_32x32x16_bf16 v[0:15], v[154:157], v[150:153], v[0:15]
	ds_read_b128 v[142:145], v130 offset:32768
	ds_read_b128 v[150:153], v228 offset:53248
	ds_read_b128 v[154:157], v130 offset:36864
	s_waitcnt lgkmcnt(2)
	v_mfma_f32_32x32x16_bf16 v[48:63], v[142:145], v[146:149], v[48:63]
	s_waitcnt lgkmcnt(1)
	v_mfma_f32_32x32x16_bf16 v[32:47], v[142:145], v[150:153], v[32:47]
	s_waitcnt lgkmcnt(0)
	v_mfma_f32_32x32x16_bf16 v[16:31], v[154:157], v[146:149], v[16:31]
	ds_read_b128 v[146:149], v229 offset:49152
	v_mfma_f32_32x32x16_bf16 v[0:15], v[154:157], v[150:153], v[0:15]
	ds_read_b128 v[142:145], v131 offset:32768
	ds_read_b128 v[150:153], v229 offset:53248
	ds_read_b128 v[154:157], v131 offset:36864
	s_waitcnt lgkmcnt(2)
	v_mfma_f32_32x32x16_bf16 v[48:63], v[142:145], v[146:149], v[48:63]
	s_waitcnt lgkmcnt(1)
	v_mfma_f32_32x32x16_bf16 v[32:47], v[142:145], v[150:153], v[32:47]
	s_waitcnt lgkmcnt(0)
	v_mfma_f32_32x32x16_bf16 v[16:31], v[154:157], v[146:149], v[16:31]
	v_mfma_f32_32x32x16_bf16 v[0:15], v[154:157], v[150:153], v[0:15]
	s_waitcnt vmcnt(24)
	ds_write_b128 v134, v[64:67]
	ds_write_b128 v134, v[80:83] offset:16384
	ds_write_b128 v134, v[68:71] offset:4096
	ds_write_b128 v134, v[84:87] offset:20480
	ds_write_b128 v134, v[72:75] offset:8192
	ds_write_b128 v134, v[88:91] offset:24576
	ds_write_b128 v134, v[76:79] offset:12288
	ds_write_b128 v134, v[92:95] offset:28672
	s_waitcnt lgkmcnt(0)
	s_barrier
	ds_read_b128 v[142:145], v128
	ds_read_b128 v[146:149], v132 offset:16384
	ds_read_b128 v[150:153], v132 offset:20480
	ds_read_b128 v[154:157], v128 offset:4096
	s_waitcnt lgkmcnt(2)
	v_mfma_f32_32x32x16_bf16 v[48:63], v[142:145], v[146:149], v[48:63]
	s_waitcnt lgkmcnt(1)
	v_mfma_f32_32x32x16_bf16 v[32:47], v[142:145], v[150:153], v[32:47]
	s_waitcnt lgkmcnt(0)
	v_mfma_f32_32x32x16_bf16 v[16:31], v[154:157], v[146:149], v[16:31]
	ds_read_b128 v[146:149], v133 offset:16384
	v_mfma_f32_32x32x16_bf16 v[0:15], v[154:157], v[150:153], v[0:15]
	ds_read_b128 v[142:145], v129
	ds_read_b128 v[150:153], v133 offset:20480
	ds_read_b128 v[154:157], v129 offset:4096
	s_waitcnt lgkmcnt(2)
	v_mfma_f32_32x32x16_bf16 v[48:63], v[142:145], v[146:149], v[48:63]
	s_waitcnt lgkmcnt(1)
	v_mfma_f32_32x32x16_bf16 v[32:47], v[142:145], v[150:153], v[32:47]
	s_waitcnt lgkmcnt(0)
	v_mfma_f32_32x32x16_bf16 v[16:31], v[154:157], v[146:149], v[16:31]
	ds_read_b128 v[146:149], v228 offset:16384
	v_mfma_f32_32x32x16_bf16 v[0:15], v[154:157], v[150:153], v[0:15]
	ds_read_b128 v[142:145], v130
	ds_read_b128 v[150:153], v228 offset:20480
	ds_read_b128 v[154:157], v130 offset:4096
	s_waitcnt lgkmcnt(2)
	v_mfma_f32_32x32x16_bf16 v[48:63], v[142:145], v[146:149], v[48:63]
	s_waitcnt lgkmcnt(1)
	v_mfma_f32_32x32x16_bf16 v[32:47], v[142:145], v[150:153], v[32:47]
	s_waitcnt lgkmcnt(0)
	v_mfma_f32_32x32x16_bf16 v[16:31], v[154:157], v[146:149], v[16:31]
	ds_read_b128 v[146:149], v229 offset:16384
	v_mfma_f32_32x32x16_bf16 v[0:15], v[154:157], v[150:153], v[0:15]
	ds_read_b128 v[142:145], v131
	ds_read_b128 v[150:153], v229 offset:20480
	ds_read_b128 v[154:157], v131 offset:4096
	s_waitcnt lgkmcnt(2)
	v_mfma_f32_32x32x16_bf16 v[48:63], v[142:145], v[146:149], v[48:63]
	s_waitcnt lgkmcnt(1)
	v_mfma_f32_32x32x16_bf16 v[32:47], v[142:145], v[150:153], v[32:47]
	s_waitcnt lgkmcnt(0)
	v_mfma_f32_32x32x16_bf16 v[16:31], v[154:157], v[146:149], v[16:31]
	v_mfma_f32_32x32x16_bf16 v[0:15], v[154:157], v[150:153], v[0:15]
	s_waitcnt vmcnt(16)
	ds_write_b128 v134, v[96:99] offset:32768
	ds_write_b128 v134, v[112:115] offset:49152
	ds_write_b128 v134, v[100:103] offset:36864
	ds_write_b128 v134, v[116:119] offset:53248
	ds_write_b128 v134, v[104:107] offset:40960
	ds_write_b128 v134, v[120:123] offset:57344
	ds_write_b128 v134, v[108:111] offset:45056
	ds_write_b128 v134, v[124:127] offset:61440
	s_waitcnt lgkmcnt(0)
	s_barrier
	ds_read_b128 v[142:145], v128 offset:32768
	ds_read_b128 v[146:149], v132 offset:49152
	ds_read_b128 v[150:153], v132 offset:53248
	ds_read_b128 v[154:157], v128 offset:36864
	s_waitcnt lgkmcnt(2)
	v_mfma_f32_32x32x16_bf16 v[48:63], v[142:145], v[146:149], v[48:63]
	s_waitcnt lgkmcnt(1)
	v_mfma_f32_32x32x16_bf16 v[32:47], v[142:145], v[150:153], v[32:47]
	s_waitcnt lgkmcnt(0)
	v_mfma_f32_32x32x16_bf16 v[16:31], v[154:157], v[146:149], v[16:31]
	ds_read_b128 v[146:149], v133 offset:49152
	v_mfma_f32_32x32x16_bf16 v[0:15], v[154:157], v[150:153], v[0:15]
	ds_read_b128 v[142:145], v129 offset:32768
	ds_read_b128 v[150:153], v133 offset:53248
	ds_read_b128 v[154:157], v129 offset:36864
	s_waitcnt lgkmcnt(2)
	v_mfma_f32_32x32x16_bf16 v[48:63], v[142:145], v[146:149], v[48:63]
	s_waitcnt lgkmcnt(1)
	v_mfma_f32_32x32x16_bf16 v[32:47], v[142:145], v[150:153], v[32:47]
	s_waitcnt lgkmcnt(0)
	v_mfma_f32_32x32x16_bf16 v[16:31], v[154:157], v[146:149], v[16:31]
	ds_read_b128 v[146:149], v228 offset:49152
	v_mfma_f32_32x32x16_bf16 v[0:15], v[154:157], v[150:153], v[0:15]
	ds_read_b128 v[142:145], v130 offset:32768
	ds_read_b128 v[150:153], v228 offset:53248
	ds_read_b128 v[154:157], v130 offset:36864
	s_waitcnt lgkmcnt(2)
	v_mfma_f32_32x32x16_bf16 v[48:63], v[142:145], v[146:149], v[48:63]
	s_waitcnt lgkmcnt(1)
	v_mfma_f32_32x32x16_bf16 v[32:47], v[142:145], v[150:153], v[32:47]
	s_waitcnt lgkmcnt(0)
	v_mfma_f32_32x32x16_bf16 v[16:31], v[154:157], v[146:149], v[16:31]
	ds_read_b128 v[146:149], v229 offset:49152
	v_mfma_f32_32x32x16_bf16 v[0:15], v[154:157], v[150:153], v[0:15]
	ds_read_b128 v[142:145], v131 offset:32768
	ds_read_b128 v[150:153], v229 offset:53248
	ds_read_b128 v[154:157], v131 offset:36864
	s_waitcnt lgkmcnt(2)
	v_mfma_f32_32x32x16_bf16 v[48:63], v[142:145], v[146:149], v[48:63]
	s_waitcnt lgkmcnt(1)
	v_mfma_f32_32x32x16_bf16 v[32:47], v[142:145], v[150:153], v[32:47]
	s_waitcnt lgkmcnt(0)
	v_mfma_f32_32x32x16_bf16 v[16:31], v[154:157], v[146:149], v[16:31]
	v_mfma_f32_32x32x16_bf16 v[0:15], v[154:157], v[150:153], v[0:15]
	s_waitcnt vmcnt(8)
	ds_write_b128 v134, v[160:163]
	ds_write_b128 v134, v[176:179] offset:16384
	ds_write_b128 v134, v[164:167] offset:4096
	ds_write_b128 v134, v[180:183] offset:20480
	ds_write_b128 v134, v[168:171] offset:8192
	ds_write_b128 v134, v[184:187] offset:24576
	ds_write_b128 v134, v[172:175] offset:12288
	ds_write_b128 v134, v[188:191] offset:28672
	s_waitcnt lgkmcnt(0)
	s_barrier
	ds_read_b128 v[142:145], v128
	ds_read_b128 v[146:149], v132 offset:16384
	ds_read_b128 v[150:153], v132 offset:20480
	ds_read_b128 v[154:157], v128 offset:4096
	s_waitcnt lgkmcnt(2)
	v_mfma_f32_32x32x16_bf16 v[48:63], v[142:145], v[146:149], v[48:63]
	s_waitcnt lgkmcnt(1)
	v_mfma_f32_32x32x16_bf16 v[32:47], v[142:145], v[150:153], v[32:47]
	s_waitcnt lgkmcnt(0)
	v_mfma_f32_32x32x16_bf16 v[16:31], v[154:157], v[146:149], v[16:31]
	ds_read_b128 v[146:149], v133 offset:16384
	v_mfma_f32_32x32x16_bf16 v[0:15], v[154:157], v[150:153], v[0:15]
	ds_read_b128 v[142:145], v129
	ds_read_b128 v[150:153], v133 offset:20480
	ds_read_b128 v[154:157], v129 offset:4096
	s_waitcnt lgkmcnt(2)
	v_mfma_f32_32x32x16_bf16 v[48:63], v[142:145], v[146:149], v[48:63]
	s_waitcnt lgkmcnt(1)
	v_mfma_f32_32x32x16_bf16 v[32:47], v[142:145], v[150:153], v[32:47]
	s_waitcnt lgkmcnt(0)
	v_mfma_f32_32x32x16_bf16 v[16:31], v[154:157], v[146:149], v[16:31]
	ds_read_b128 v[146:149], v228 offset:16384
	v_mfma_f32_32x32x16_bf16 v[0:15], v[154:157], v[150:153], v[0:15]
	ds_read_b128 v[142:145], v130
	ds_read_b128 v[150:153], v228 offset:20480
	ds_read_b128 v[154:157], v130 offset:4096
	s_waitcnt lgkmcnt(2)
	v_mfma_f32_32x32x16_bf16 v[48:63], v[142:145], v[146:149], v[48:63]
	s_waitcnt lgkmcnt(1)
	v_mfma_f32_32x32x16_bf16 v[32:47], v[142:145], v[150:153], v[32:47]
	s_waitcnt lgkmcnt(0)
	v_mfma_f32_32x32x16_bf16 v[16:31], v[154:157], v[146:149], v[16:31]
	ds_read_b128 v[146:149], v229 offset:16384
	v_mfma_f32_32x32x16_bf16 v[0:15], v[154:157], v[150:153], v[0:15]
	ds_read_b128 v[142:145], v131
	ds_read_b128 v[150:153], v229 offset:20480
	ds_read_b128 v[154:157], v131 offset:4096
	s_waitcnt lgkmcnt(2)
	v_mfma_f32_32x32x16_bf16 v[48:63], v[142:145], v[146:149], v[48:63]
	s_waitcnt lgkmcnt(1)
	v_mfma_f32_32x32x16_bf16 v[32:47], v[142:145], v[150:153], v[32:47]
	s_waitcnt lgkmcnt(0)
	v_mfma_f32_32x32x16_bf16 v[16:31], v[154:157], v[146:149], v[16:31]
	v_mfma_f32_32x32x16_bf16 v[0:15], v[154:157], v[150:153], v[0:15]
	s_waitcnt vmcnt(0)
	ds_write_b128 v134, v[196:199] offset:32768
	ds_write_b128 v134, v[212:215] offset:49152
	ds_write_b128 v134, v[200:203] offset:36864
	ds_write_b128 v134, v[216:219] offset:53248
	ds_write_b128 v134, v[204:207] offset:40960
	ds_write_b128 v134, v[220:223] offset:57344
	ds_write_b128 v134, v[208:211] offset:45056
	ds_write_b128 v134, v[224:227] offset:61440
	s_waitcnt lgkmcnt(0)
	s_barrier
	ds_read_b128 v[142:145], v128 offset:32768
	ds_read_b128 v[146:149], v132 offset:49152
	ds_read_b128 v[150:153], v132 offset:53248
	ds_read_b128 v[154:157], v128 offset:36864
	s_waitcnt lgkmcnt(2)
	v_mfma_f32_32x32x16_bf16 v[48:63], v[142:145], v[146:149], v[48:63]
	s_waitcnt lgkmcnt(1)
	v_mfma_f32_32x32x16_bf16 v[32:47], v[142:145], v[150:153], v[32:47]
	s_waitcnt lgkmcnt(0)
	v_mfma_f32_32x32x16_bf16 v[16:31], v[154:157], v[146:149], v[16:31]
	ds_read_b128 v[146:149], v133 offset:49152
	v_mfma_f32_32x32x16_bf16 v[0:15], v[154:157], v[150:153], v[0:15]
	ds_read_b128 v[142:145], v129 offset:32768
	ds_read_b128 v[150:153], v133 offset:53248
	ds_read_b128 v[154:157], v129 offset:36864
	s_waitcnt lgkmcnt(2)
	v_mfma_f32_32x32x16_bf16 v[48:63], v[142:145], v[146:149], v[48:63]
	s_waitcnt lgkmcnt(1)
	v_mfma_f32_32x32x16_bf16 v[32:47], v[142:145], v[150:153], v[32:47]
	s_waitcnt lgkmcnt(0)
	v_mfma_f32_32x32x16_bf16 v[16:31], v[154:157], v[146:149], v[16:31]
	ds_read_b128 v[146:149], v228 offset:49152
	v_mfma_f32_32x32x16_bf16 v[0:15], v[154:157], v[150:153], v[0:15]
	ds_read_b128 v[142:145], v130 offset:32768
	ds_read_b128 v[150:153], v228 offset:53248
	ds_read_b128 v[154:157], v130 offset:36864
	s_waitcnt lgkmcnt(2)
	v_mfma_f32_32x32x16_bf16 v[48:63], v[142:145], v[146:149], v[48:63]
	s_waitcnt lgkmcnt(1)
	v_mfma_f32_32x32x16_bf16 v[32:47], v[142:145], v[150:153], v[32:47]
	s_waitcnt lgkmcnt(0)
	v_mfma_f32_32x32x16_bf16 v[16:31], v[154:157], v[146:149], v[16:31]
	ds_read_b128 v[146:149], v229 offset:49152
	v_mfma_f32_32x32x16_bf16 v[0:15], v[154:157], v[150:153], v[0:15]
	ds_read_b128 v[142:145], v131 offset:32768
	ds_read_b128 v[150:153], v229 offset:53248
	ds_read_b128 v[154:157], v131 offset:36864
	s_waitcnt lgkmcnt(2)
	v_mfma_f32_32x32x16_bf16 v[48:63], v[142:145], v[146:149], v[48:63]
	s_waitcnt lgkmcnt(1)
	v_mfma_f32_32x32x16_bf16 v[32:47], v[142:145], v[150:153], v[32:47]
	s_waitcnt lgkmcnt(0)
	v_mfma_f32_32x32x16_bf16 v[16:31], v[154:157], v[146:149], v[16:31]
	v_mfma_f32_32x32x16_bf16 v[0:15], v[154:157], v[150:153], v[0:15]
	s_barrier
	s_branch .Lsha_s5y_j
.Lsha_s5y_h1:
	global_load_dwordx4 v[80:83], v231, s[22:23]
	global_load_dwordx4 v[84:87], v231, s[54:55]
	global_load_dwordx4 v[88:91], v231, s[72:73]
	global_load_dwordx4 v[92:95], v231, s[74:75]
	global_load_dwordx4 v[112:115], v231, s[22:23] offset:128
	global_load_dwordx4 v[116:119], v231, s[54:55] offset:128
	global_load_dwordx4 v[120:123], v231, s[72:73] offset:128
	global_load_dwordx4 v[124:127], v231, s[74:75] offset:128
	global_load_dwordx4 v[176:179], v231, s[22:23] offset:256
	global_load_dwordx4 v[180:183], v231, s[54:55] offset:256
	global_load_dwordx4 v[184:187], v231, s[72:73] offset:256
	global_load_dwordx4 v[188:191], v231, s[74:75] offset:256
	global_load_dwordx4 v[212:215], v231, s[22:23] offset:384
	global_load_dwordx4 v[216:219], v231, s[54:55] offset:384
	global_load_dwordx4 v[220:223], v231, s[72:73] offset:384
	global_load_dwordx4 v[224:227], v231, s[74:75] offset:384
	v_add_u32_e32 v128, v135, v137
	v_add_u32_e32 v132, v136, v137
	v_add_u32_e32 v129, v135, v138
	v_add_u32_e32 v133, v136, v138
	v_add_u32_e32 v130, v135, v139
	v_add_u32_e32 v228, v136, v139
	v_add_u32_e32 v131, v135, v140
	v_add_u32_e32 v128, 0xffff0000, v128
	v_add_u32_e32 v129, 0xffff0000, v129
	v_add_u32_e32 v130, 0xffff0000, v130
	v_add_u32_e32 v131, 0xffff0000, v131
	v_add_u32_e32 v229, v136, v140
	v_mov_b32_e32 v0, 0
	v_mov_b32_e32 v1, v0
	v_mov_b32_e32 v2, v0
	v_mov_b32_e32 v3, v0
	v_mov_b32_e32 v4, v0
	v_mov_b32_e32 v5, v0
	v_mov_b32_e32 v6, v0
	v_mov_b32_e32 v7, v0
	v_mov_b32_e32 v8, v0
	v_mov_b32_e32 v9, v0
	v_mov_b32_e32 v10, v0
	v_mov_b32_e32 v11, v0
	v_mov_b32_e32 v12, v0
	v_mov_b32_e32 v13, v0
	v_mov_b32_e32 v14, v0
	v_mov_b32_e32 v15, v0
	v_mov_b32_e32 v16, v0
	v_mov_b32_e32 v17, v0
	v_mov_b32_e32 v18, v0
	v_mov_b32_e32 v19, v0
	v_mov_b32_e32 v20, v0
	v_mov_b32_e32 v21, v0
	v_mov_b32_e32 v22, v0
	v_mov_b32_e32 v23, v0
	v_mov_b32_e32 v24, v0
	v_mov_b32_e32 v25, v0
	v_mov_b32_e32 v26, v0
	v_mov_b32_e32 v27, v0
	v_mov_b32_e32 v28, v0
	v_mov_b32_e32 v29, v0
	v_mov_b32_e32 v30, v0
	v_mov_b32_e32 v31, v0
	v_mov_b32_e32 v32, v0
	v_mov_b32_e32 v33, v0
	v_mov_b32_e32 v34, v0
	v_mov_b32_e32 v35, v0
	v_mov_b32_e32 v36, v0
	v_mov_b32_e32 v37, v0
	v_mov_b32_e32 v38, v0
	v_mov_b32_e32 v39, v0
	v_mov_b32_e32 v40, v0
	v_mov_b32_e32 v41, v0
	v_mov_b32_e32 v42, v0
	v_mov_b32_e32 v43, v0
	v_mov_b32_e32 v44, v0
	v_mov_b32_e32 v45, v0
	v_mov_b32_e32 v46, v0
	v_mov_b32_e32 v47, v0
	v_mov_b32_e32 v48, v0
	v_mov_b32_e32 v49, v0
	v_mov_b32_e32 v50, v0
	v_mov_b32_e32 v51, v0
	v_mov_b32_e32 v52, v0
	v_mov_b32_e32 v53, v0
	v_mov_b32_e32 v54, v0
	v_mov_b32_e32 v55, v0
	v_mov_b32_e32 v56, v0
	v_mov_b32_e32 v57, v0
	v_mov_b32_e32 v58, v0
	v_mov_b32_e32 v59, v0
	v_mov_b32_e32 v60, v0
	v_mov_b32_e32 v61, v0
	v_mov_b32_e32 v62, v0
	v_mov_b32_e32 v63, v0
	s_waitcnt vmcnt(12)
	ds_write_b128 v134, v[80:83] offset:16384
	ds_write_b128 v134, v[84:87] offset:20480
	ds_write_b128 v134, v[88:91] offset:24576
	ds_write_b128 v134, v[92:95] offset:28672
	s_waitcnt lgkmcnt(0)
	s_barrier
	global_load_dwordx4 v[80:83], v231, s[22:23] offset:512
	global_load_dwordx4 v[84:87], v231, s[54:55] offset:512
	global_load_dwordx4 v[88:91], v231, s[72:73] offset:512
	global_load_dwordx4 v[92:95], v231, s[74:75] offset:512
	ds_read_b128 v[142:145], v128
	ds_read_b128 v[146:149], v132 offset:16384
	ds_read_b128 v[150:153], v132 offset:20480
	ds_read_b128 v[154:157], v128 offset:4096
	s_waitcnt lgkmcnt(2)
	v_mfma_f32_32x32x16_bf16 v[48:63], v[142:145], v[146:149], v[48:63]
	s_waitcnt lgkmcnt(1)
	v_mfma_f32_32x32x16_bf16 v[32:47], v[142:145], v[150:153], v[32:47]
	s_waitcnt lgkmcnt(0)
	v_mfma_f32_32x32x16_bf16 v[16:31], v[154:157], v[146:149], v[16:31]
	ds_read_b128 v[146:149], v133 offset:16384
	v_mfma_f32_32x32x16_bf16 v[0:15], v[154:157], v[150:153], v[0:15]
	ds_read_b128 v[142:145], v129
	ds_read_b128 v[150:153], v133 offset:20480
	ds_read_b128 v[154:157], v129 offset:4096
	s_waitcnt lgkmcnt(2)
	v_mfma_f32_32x32x16_bf16 v[48:63], v[142:145], v[146:149], v[48:63]
	s_waitcnt lgkmcnt(1)
	v_mfma_f32_32x32x16_bf16 v[32:47], v[142:145], v[150:153], v[32:47]
	s_waitcnt lgkmcnt(0)
	v_mfma_f32_32x32x16_bf16 v[16:31], v[154:157], v[146:149], v[16:31]
	ds_read_b128 v[146:149], v228 offset:16384
	v_mfma_f32_32x32x16_bf16 v[0:15], v[154:157], v[150:153], v[0:15]
	ds_read_b128 v[142:145], v130
	ds_read_b128 v[150:153], v228 offset:20480
	ds_read_b128 v[154:157], v130 offset:4096
	s_waitcnt lgkmcnt(2)
	v_mfma_f32_32x32x16_bf16 v[48:63], v[142:145], v[146:149], v[48:63]
	s_waitcnt lgkmcnt(1)
	v_mfma_f32_32x32x16_bf16 v[32:47], v[142:145], v[150:153], v[32:47]
	s_waitcnt lgkmcnt(0)
	v_mfma_f32_32x32x16_bf16 v[16:31], v[154:157], v[146:149], v[16:31]
	ds_read_b128 v[146:149], v229 offset:16384
	v_mfma_f32_32x32x16_bf16 v[0:15], v[154:157], v[150:153], v[0:15]
	ds_read_b128 v[142:145], v131
	ds_read_b128 v[150:153], v229 offset:20480
	ds_read_b128 v[154:157], v131 offset:4096
	s_waitcnt lgkmcnt(2)
	v_mfma_f32_32x32x16_bf16 v[48:63], v[142:145], v[146:149], v[48:63]
	s_waitcnt lgkmcnt(1)
	v_mfma_f32_32x32x16_bf16 v[32:47], v[142:145], v[150:153], v[32:47]
	s_waitcnt lgkmcnt(0)
	v_mfma_f32_32x32x16_bf16 v[16:31], v[154:157], v[146:149], v[16:31]
	v_mfma_f32_32x32x16_bf16 v[0:15], v[154:157], v[150:153], v[0:15]
	s_waitcnt vmcnt(12)
	ds_write_b128 v134, v[112:115] offset:49152
	ds_write_b128 v134, v[116:119] offset:53248
	ds_write_b128 v134, v[120:123] offset:57344
	ds_write_b128 v134, v[124:127] offset:61440
	s_waitcnt lgkmcnt(0)
	s_barrier
	global_load_dwordx4 v[112:115], v231, s[22:23] offset:640
	global_load_dwordx4 v[116:119], v231, s[54:55] offset:640
	global_load_dwordx4 v[120:123], v231, s[72:73] offset:640
	global_load_dwordx4 v[124:127], v231, s[74:75] offset:640
	ds_read_b128 v[142:145], v128 offset:32768
	ds_read_b128 v[146:149], v132 offset:49152
	ds_read_b128 v[150:153], v132 offset:53248
	ds_read_b128 v[154:157], v128 offset:36864
	s_waitcnt lgkmcnt(2)
	v_mfma_f32_32x32x16_bf16 v[48:63], v[142:145], v[146:149], v[48:63]
	s_waitcnt lgkmcnt(1)
	v_mfma_f32_32x32x16_bf16 v[32:47], v[142:145], v[150:153], v[32:47]
	s_waitcnt lgkmcnt(0)
	v_mfma_f32_32x32x16_bf16 v[16:31], v[154:157], v[146:149], v[16:31]
	ds_read_b128 v[146:149], v133 offset:49152
	v_mfma_f32_32x32x16_bf16 v[0:15], v[154:157], v[150:153], v[0:15]
	ds_read_b128 v[142:145], v129 offset:32768
	ds_read_b128 v[150:153], v133 offset:53248
	ds_read_b128 v[154:157], v129 offset:36864
	s_waitcnt lgkmcnt(2)
	v_mfma_f32_32x32x16_bf16 v[48:63], v[142:145], v[146:149], v[48:63]
	s_waitcnt lgkmcnt(1)
	v_mfma_f32_32x32x16_bf16 v[32:47], v[142:145], v[150:153], v[32:47]
	s_waitcnt lgkmcnt(0)
	v_mfma_f32_32x32x16_bf16 v[16:31], v[154:157], v[146:149], v[16:31]
	ds_read_b128 v[146:149], v228 offset:49152
	v_mfma_f32_32x32x16_bf16 v[0:15], v[154:157], v[150:153], v[0:15]
	ds_read_b128 v[142:145], v130 offset:32768
	ds_read_b128 v[150:153], v228 offset:53248
	ds_read_b128 v[154:157], v130 offset:36864
	s_waitcnt lgkmcnt(2)
	v_mfma_f32_32x32x16_bf16 v[48:63], v[142:145], v[146:149], v[48:63]
	s_waitcnt lgkmcnt(1)
	v_mfma_f32_32x32x16_bf16 v[32:47], v[142:145], v[150:153], v[32:47]
	s_waitcnt lgkmcnt(0)
	v_mfma_f32_32x32x16_bf16 v[16:31], v[154:157], v[146:149], v[16:31]
	ds_read_b128 v[146:149], v229 offset:49152
	v_mfma_f32_32x32x16_bf16 v[0:15], v[154:157], v[150:153], v[0:15]
	ds_read_b128 v[142:145], v131 offset:32768
	ds_read_b128 v[150:153], v229 offset:53248
	ds_read_b128 v[154:157], v131 offset:36864
	s_waitcnt lgkmcnt(2)
	v_mfma_f32_32x32x16_bf16 v[48:63], v[142:145], v[146:149], v[48:63]
	s_waitcnt lgkmcnt(1)
	v_mfma_f32_32x32x16_bf16 v[32:47], v[142:145], v[150:153], v[32:47]
	s_waitcnt lgkmcnt(0)
	v_mfma_f32_32x32x16_bf16 v[16:31], v[154:157], v[146:149], v[16:31]
	v_mfma_f32_32x32x16_bf16 v[0:15], v[154:157], v[150:153], v[0:15]
	s_waitcnt vmcnt(12)
	ds_write_b128 v134, v[176:179] offset:16384
	ds_write_b128 v134, v[180:183] offset:20480
	ds_write_b128 v134, v[184:187] offset:24576
	ds_write_b128 v134, v[188:191] offset:28672
	s_waitcnt lgkmcnt(0)
	s_barrier
	global_load_dwordx4 v[176:179], v231, s[22:23] offset:768
	global_load_dwordx4 v[180:183], v231, s[54:55] offset:768
	global_load_dwordx4 v[184:187], v231, s[72:73] offset:768
	global_load_dwordx4 v[188:191], v231, s[74:75] offset:768
	ds_read_b128 v[142:145], v128
	ds_read_b128 v[146:149], v132 offset:16384
	ds_read_b128 v[150:153], v132 offset:20480
	ds_read_b128 v[154:157], v128 offset:4096
	s_waitcnt lgkmcnt(2)
	v_mfma_f32_32x32x16_bf16 v[48:63], v[142:145], v[146:149], v[48:63]
	s_waitcnt lgkmcnt(1)
	v_mfma_f32_32x32x16_bf16 v[32:47], v[142:145], v[150:153], v[32:47]
	s_waitcnt lgkmcnt(0)
	v_mfma_f32_32x32x16_bf16 v[16:31], v[154:157], v[146:149], v[16:31]
	ds_read_b128 v[146:149], v133 offset:16384
	v_mfma_f32_32x32x16_bf16 v[0:15], v[154:157], v[150:153], v[0:15]
	ds_read_b128 v[142:145], v129
	ds_read_b128 v[150:153], v133 offset:20480
	ds_read_b128 v[154:157], v129 offset:4096
	s_waitcnt lgkmcnt(2)
	v_mfma_f32_32x32x16_bf16 v[48:63], v[142:145], v[146:149], v[48:63]
	s_waitcnt lgkmcnt(1)
	v_mfma_f32_32x32x16_bf16 v[32:47], v[142:145], v[150:153], v[32:47]
	s_waitcnt lgkmcnt(0)
	v_mfma_f32_32x32x16_bf16 v[16:31], v[154:157], v[146:149], v[16:31]
	ds_read_b128 v[146:149], v228 offset:16384
	v_mfma_f32_32x32x16_bf16 v[0:15], v[154:157], v[150:153], v[0:15]
	ds_read_b128 v[142:145], v130
	ds_read_b128 v[150:153], v228 offset:20480
	ds_read_b128 v[154:157], v130 offset:4096
	s_waitcnt lgkmcnt(2)
	v_mfma_f32_32x32x16_bf16 v[48:63], v[142:145], v[146:149], v[48:63]
	s_waitcnt lgkmcnt(1)
	v_mfma_f32_32x32x16_bf16 v[32:47], v[142:145], v[150:153], v[32:47]
	s_waitcnt lgkmcnt(0)
	v_mfma_f32_32x32x16_bf16 v[16:31], v[154:157], v[146:149], v[16:31]
	ds_read_b128 v[146:149], v229 offset:16384
	v_mfma_f32_32x32x16_bf16 v[0:15], v[154:157], v[150:153], v[0:15]
	ds_read_b128 v[142:145], v131
	ds_read_b128 v[150:153], v229 offset:20480
	ds_read_b128 v[154:157], v131 offset:4096
	s_waitcnt lgkmcnt(2)
	v_mfma_f32_32x32x16_bf16 v[48:63], v[142:145], v[146:149], v[48:63]
	s_waitcnt lgkmcnt(1)
	v_mfma_f32_32x32x16_bf16 v[32:47], v[142:145], v[150:153], v[32:47]
	s_waitcnt lgkmcnt(0)
	v_mfma_f32_32x32x16_bf16 v[16:31], v[154:157], v[146:149], v[16:31]
	v_mfma_f32_32x32x16_bf16 v[0:15], v[154:157], v[150:153], v[0:15]
	s_waitcnt vmcnt(12)
	ds_write_b128 v134, v[212:215] offset:49152
	ds_write_b128 v134, v[216:219] offset:53248
	ds_write_b128 v134, v[220:223] offset:57344
	ds_write_b128 v134, v[224:227] offset:61440
	s_waitcnt lgkmcnt(0)
	s_barrier
	global_load_dwordx4 v[212:215], v231, s[22:23] offset:896
	global_load_dwordx4 v[216:219], v231, s[54:55] offset:896
	global_load_dwordx4 v[220:223], v231, s[72:73] offset:896
	global_load_dwordx4 v[224:227], v231, s[74:75] offset:896
	ds_read_b128 v[142:145], v128 offset:32768
	ds_read_b128 v[146:149], v132 offset:49152
	ds_read_b128 v[150:153], v132 offset:53248
	ds_read_b128 v[154:157], v128 offset:36864
	s_waitcnt lgkmcnt(2)
	v_mfma_f32_32x32x16_bf16 v[48:63], v[142:145], v[146:149], v[48:63]
	s_waitcnt lgkmcnt(1)
	v_mfma_f32_32x32x16_bf16 v[32:47], v[142:145], v[150:153], v[32:47]
	s_waitcnt lgkmcnt(0)
	v_mfma_f32_32x32x16_bf16 v[16:31], v[154:157], v[146:149], v[16:31]
	ds_read_b128 v[146:149], v133 offset:49152
	v_mfma_f32_32x32x16_bf16 v[0:15], v[154:157], v[150:153], v[0:15]
	ds_read_b128 v[142:145], v129 offset:32768
	ds_read_b128 v[150:153], v133 offset:53248
	ds_read_b128 v[154:157], v129 offset:36864
	s_waitcnt lgkmcnt(2)
	v_mfma_f32_32x32x16_bf16 v[48:63], v[142:145], v[146:149], v[48:63]
	s_waitcnt lgkmcnt(1)
	v_mfma_f32_32x32x16_bf16 v[32:47], v[142:145], v[150:153], v[32:47]
	s_waitcnt lgkmcnt(0)
	v_mfma_f32_32x32x16_bf16 v[16:31], v[154:157], v[146:149], v[16:31]
	ds_read_b128 v[146:149], v228 offset:49152
	v_mfma_f32_32x32x16_bf16 v[0:15], v[154:157], v[150:153], v[0:15]
	ds_read_b128 v[142:145], v130 offset:32768
	ds_read_b128 v[150:153], v228 offset:53248
	ds_read_b128 v[154:157], v130 offset:36864
	s_waitcnt lgkmcnt(2)
	v_mfma_f32_32x32x16_bf16 v[48:63], v[142:145], v[146:149], v[48:63]
	s_waitcnt lgkmcnt(1)
	v_mfma_f32_32x32x16_bf16 v[32:47], v[142:145], v[150:153], v[32:47]
	s_waitcnt lgkmcnt(0)
	v_mfma_f32_32x32x16_bf16 v[16:31], v[154:157], v[146:149], v[16:31]
	ds_read_b128 v[146:149], v229 offset:49152
	v_mfma_f32_32x32x16_bf16 v[0:15], v[154:157], v[150:153], v[0:15]
	ds_read_b128 v[142:145], v131 offset:32768
	ds_read_b128 v[150:153], v229 offset:53248
	ds_read_b128 v[154:157], v131 offset:36864
	s_waitcnt lgkmcnt(2)
	v_mfma_f32_32x32x16_bf16 v[48:63], v[142:145], v[146:149], v[48:63]
	s_waitcnt lgkmcnt(1)
	v_mfma_f32_32x32x16_bf16 v[32:47], v[142:145], v[150:153], v[32:47]
	s_waitcnt lgkmcnt(0)
	v_mfma_f32_32x32x16_bf16 v[16:31], v[154:157], v[146:149], v[16:31]
	v_mfma_f32_32x32x16_bf16 v[0:15], v[154:157], v[150:153], v[0:15]
	s_waitcnt vmcnt(12)
	ds_write_b128 v134, v[80:83] offset:16384
	ds_write_b128 v134, v[84:87] offset:20480
	ds_write_b128 v134, v[88:91] offset:24576
	ds_write_b128 v134, v[92:95] offset:28672
	s_waitcnt lgkmcnt(0)
	s_barrier
	global_load_dwordx4 v[80:83], v231, s[22:23] offset:1024
	global_load_dwordx4 v[84:87], v231, s[54:55] offset:1024
	global_load_dwordx4 v[88:91], v231, s[72:73] offset:1024
	global_load_dwordx4 v[92:95], v231, s[74:75] offset:1024
	ds_read_b128 v[142:145], v128
	ds_read_b128 v[146:149], v132 offset:16384
	ds_read_b128 v[150:153], v132 offset:20480
	ds_read_b128 v[154:157], v128 offset:4096
	s_waitcnt lgkmcnt(2)
	v_mfma_f32_32x32x16_bf16 v[48:63], v[142:145], v[146:149], v[48:63]
	s_waitcnt lgkmcnt(1)
	v_mfma_f32_32x32x16_bf16 v[32:47], v[142:145], v[150:153], v[32:47]
	s_waitcnt lgkmcnt(0)
	v_mfma_f32_32x32x16_bf16 v[16:31], v[154:157], v[146:149], v[16:31]
	ds_read_b128 v[146:149], v133 offset:16384
	v_mfma_f32_32x32x16_bf16 v[0:15], v[154:157], v[150:153], v[0:15]
	ds_read_b128 v[142:145], v129
	ds_read_b128 v[150:153], v133 offset:20480
	ds_read_b128 v[154:157], v129 offset:4096
	s_waitcnt lgkmcnt(2)
	v_mfma_f32_32x32x16_bf16 v[48:63], v[142:145], v[146:149], v[48:63]
	s_waitcnt lgkmcnt(1)
	v_mfma_f32_32x32x16_bf16 v[32:47], v[142:145], v[150:153], v[32:47]
	s_waitcnt lgkmcnt(0)
	v_mfma_f32_32x32x16_bf16 v[16:31], v[154:157], v[146:149], v[16:31]
	ds_read_b128 v[146:149], v228 offset:16384
	v_mfma_f32_32x32x16_bf16 v[0:15], v[154:157], v[150:153], v[0:15]
	ds_read_b128 v[142:145], v130
	ds_read_b128 v[150:153], v228 offset:20480
	ds_read_b128 v[154:157], v130 offset:4096
	s_waitcnt lgkmcnt(2)
	v_mfma_f32_32x32x16_bf16 v[48:63], v[142:145], v[146:149], v[48:63]
	s_waitcnt lgkmcnt(1)
	v_mfma_f32_32x32x16_bf16 v[32:47], v[142:145], v[150:153], v[32:47]
	s_waitcnt lgkmcnt(0)
	v_mfma_f32_32x32x16_bf16 v[16:31], v[154:157], v[146:149], v[16:31]
	ds_read_b128 v[146:149], v229 offset:16384
	v_mfma_f32_32x32x16_bf16 v[0:15], v[154:157], v[150:153], v[0:15]
	ds_read_b128 v[142:145], v131
	ds_read_b128 v[150:153], v229 offset:20480
	ds_read_b128 v[154:157], v131 offset:4096
	s_waitcnt lgkmcnt(2)
	v_mfma_f32_32x32x16_bf16 v[48:63], v[142:145], v[146:149], v[48:63]
	s_waitcnt lgkmcnt(1)
	v_mfma_f32_32x32x16_bf16 v[32:47], v[142:145], v[150:153], v[32:47]
	s_waitcnt lgkmcnt(0)
	v_mfma_f32_32x32x16_bf16 v[16:31], v[154:157], v[146:149], v[16:31]
	v_mfma_f32_32x32x16_bf16 v[0:15], v[154:157], v[150:153], v[0:15]
	s_waitcnt vmcnt(12)
	ds_write_b128 v134, v[112:115] offset:49152
	ds_write_b128 v134, v[116:119] offset:53248
	ds_write_b128 v134, v[120:123] offset:57344
	ds_write_b128 v134, v[124:127] offset:61440
	s_waitcnt lgkmcnt(0)
	s_barrier
	global_load_dwordx4 v[112:115], v231, s[22:23] offset:1152
	global_load_dwordx4 v[116:119], v231, s[54:55] offset:1152
	global_load_dwordx4 v[120:123], v231, s[72:73] offset:1152
	global_load_dwordx4 v[124:127], v231, s[74:75] offset:1152
	ds_read_b128 v[142:145], v128 offset:32768
	ds_read_b128 v[146:149], v132 offset:49152
	ds_read_b128 v[150:153], v132 offset:53248
	ds_read_b128 v[154:157], v128 offset:36864
	s_waitcnt lgkmcnt(2)
	v_mfma_f32_32x32x16_bf16 v[48:63], v[142:145], v[146:149], v[48:63]
	s_waitcnt lgkmcnt(1)
	v_mfma_f32_32x32x16_bf16 v[32:47], v[142:145], v[150:153], v[32:47]
	s_waitcnt lgkmcnt(0)
	v_mfma_f32_32x32x16_bf16 v[16:31], v[154:157], v[146:149], v[16:31]
	ds_read_b128 v[146:149], v133 offset:49152
	v_mfma_f32_32x32x16_bf16 v[0:15], v[154:157], v[150:153], v[0:15]
	ds_read_b128 v[142:145], v129 offset:32768
	ds_read_b128 v[150:153], v133 offset:53248
	ds_read_b128 v[154:157], v129 offset:36864
	s_waitcnt lgkmcnt(2)
	v_mfma_f32_32x32x16_bf16 v[48:63], v[142:145], v[146:149], v[48:63]
	s_waitcnt lgkmcnt(1)
	v_mfma_f32_32x32x16_bf16 v[32:47], v[142:145], v[150:153], v[32:47]
	s_waitcnt lgkmcnt(0)
	v_mfma_f32_32x32x16_bf16 v[16:31], v[154:157], v[146:149], v[16:31]
	ds_read_b128 v[146:149], v228 offset:49152
	v_mfma_f32_32x32x16_bf16 v[0:15], v[154:157], v[150:153], v[0:15]
	ds_read_b128 v[142:145], v130 offset:32768
	ds_read_b128 v[150:153], v228 offset:53248
	ds_read_b128 v[154:157], v130 offset:36864
	s_waitcnt lgkmcnt(2)
	v_mfma_f32_32x32x16_bf16 v[48:63], v[142:145], v[146:149], v[48:63]
	s_waitcnt lgkmcnt(1)
	v_mfma_f32_32x32x16_bf16 v[32:47], v[142:145], v[150:153], v[32:47]
	s_waitcnt lgkmcnt(0)
	v_mfma_f32_32x32x16_bf16 v[16:31], v[154:157], v[146:149], v[16:31]
	ds_read_b128 v[146:149], v229 offset:49152
	v_mfma_f32_32x32x16_bf16 v[0:15], v[154:157], v[150:153], v[0:15]
	ds_read_b128 v[142:145], v131 offset:32768
	ds_read_b128 v[150:153], v229 offset:53248
	ds_read_b128 v[154:157], v131 offset:36864
	s_waitcnt lgkmcnt(2)
	v_mfma_f32_32x32x16_bf16 v[48:63], v[142:145], v[146:149], v[48:63]
	s_waitcnt lgkmcnt(1)
	v_mfma_f32_32x32x16_bf16 v[32:47], v[142:145], v[150:153], v[32:47]
	s_waitcnt lgkmcnt(0)
	v_mfma_f32_32x32x16_bf16 v[16:31], v[154:157], v[146:149], v[16:31]
	v_mfma_f32_32x32x16_bf16 v[0:15], v[154:157], v[150:153], v[0:15]
	s_waitcnt vmcnt(12)
	ds_write_b128 v134, v[176:179] offset:16384
	ds_write_b128 v134, v[180:183] offset:20480
	ds_write_b128 v134, v[184:187] offset:24576
	ds_write_b128 v134, v[188:191] offset:28672
	s_waitcnt lgkmcnt(0)
	s_barrier
	global_load_dwordx4 v[176:179], v231, s[22:23] offset:1280
	global_load_dwordx4 v[180:183], v231, s[54:55] offset:1280
	global_load_dwordx4 v[184:187], v231, s[72:73] offset:1280
	global_load_dwordx4 v[188:191], v231, s[74:75] offset:1280
	ds_read_b128 v[142:145], v128
	ds_read_b128 v[146:149], v132 offset:16384
	ds_read_b128 v[150:153], v132 offset:20480
	ds_read_b128 v[154:157], v128 offset:4096
	s_waitcnt lgkmcnt(2)
	v_mfma_f32_32x32x16_bf16 v[48:63], v[142:145], v[146:149], v[48:63]
	s_waitcnt lgkmcnt(1)
	v_mfma_f32_32x32x16_bf16 v[32:47], v[142:145], v[150:153], v[32:47]
	s_waitcnt lgkmcnt(0)
	v_mfma_f32_32x32x16_bf16 v[16:31], v[154:157], v[146:149], v[16:31]
	ds_read_b128 v[146:149], v133 offset:16384
	v_mfma_f32_32x32x16_bf16 v[0:15], v[154:157], v[150:153], v[0:15]
	ds_read_b128 v[142:145], v129
	ds_read_b128 v[150:153], v133 offset:20480
	ds_read_b128 v[154:157], v129 offset:4096
	s_waitcnt lgkmcnt(2)
	v_mfma_f32_32x32x16_bf16 v[48:63], v[142:145], v[146:149], v[48:63]
	s_waitcnt lgkmcnt(1)
	v_mfma_f32_32x32x16_bf16 v[32:47], v[142:145], v[150:153], v[32:47]
	s_waitcnt lgkmcnt(0)
	v_mfma_f32_32x32x16_bf16 v[16:31], v[154:157], v[146:149], v[16:31]
	ds_read_b128 v[146:149], v228 offset:16384
	v_mfma_f32_32x32x16_bf16 v[0:15], v[154:157], v[150:153], v[0:15]
	ds_read_b128 v[142:145], v130
	ds_read_b128 v[150:153], v228 offset:20480
	ds_read_b128 v[154:157], v130 offset:4096
	s_waitcnt lgkmcnt(2)
	v_mfma_f32_32x32x16_bf16 v[48:63], v[142:145], v[146:149], v[48:63]
	s_waitcnt lgkmcnt(1)
	v_mfma_f32_32x32x16_bf16 v[32:47], v[142:145], v[150:153], v[32:47]
	s_waitcnt lgkmcnt(0)
	v_mfma_f32_32x32x16_bf16 v[16:31], v[154:157], v[146:149], v[16:31]
	ds_read_b128 v[146:149], v229 offset:16384
	v_mfma_f32_32x32x16_bf16 v[0:15], v[154:157], v[150:153], v[0:15]
	ds_read_b128 v[142:145], v131
	ds_read_b128 v[150:153], v229 offset:20480
	ds_read_b128 v[154:157], v131 offset:4096
	s_waitcnt lgkmcnt(2)
	v_mfma_f32_32x32x16_bf16 v[48:63], v[142:145], v[146:149], v[48:63]
	s_waitcnt lgkmcnt(1)
	v_mfma_f32_32x32x16_bf16 v[32:47], v[142:145], v[150:153], v[32:47]
	s_waitcnt lgkmcnt(0)
	v_mfma_f32_32x32x16_bf16 v[16:31], v[154:157], v[146:149], v[16:31]
	v_mfma_f32_32x32x16_bf16 v[0:15], v[154:157], v[150:153], v[0:15]
	s_waitcnt vmcnt(12)
	ds_write_b128 v134, v[212:215] offset:49152
	ds_write_b128 v134, v[216:219] offset:53248
	ds_write_b128 v134, v[220:223] offset:57344
	ds_write_b128 v134, v[224:227] offset:61440
	s_waitcnt lgkmcnt(0)
	s_barrier
	global_load_dwordx4 v[212:215], v231, s[22:23] offset:1408
	global_load_dwordx4 v[216:219], v231, s[54:55] offset:1408
	global_load_dwordx4 v[220:223], v231, s[72:73] offset:1408
	global_load_dwordx4 v[224:227], v231, s[74:75] offset:1408
	ds_read_b128 v[142:145], v128 offset:32768
	ds_read_b128 v[146:149], v132 offset:49152
	ds_read_b128 v[150:153], v132 offset:53248
	ds_read_b128 v[154:157], v128 offset:36864
	s_waitcnt lgkmcnt(2)
	v_mfma_f32_32x32x16_bf16 v[48:63], v[142:145], v[146:149], v[48:63]
	s_waitcnt lgkmcnt(1)
	v_mfma_f32_32x32x16_bf16 v[32:47], v[142:145], v[150:153], v[32:47]
	s_waitcnt lgkmcnt(0)
	v_mfma_f32_32x32x16_bf16 v[16:31], v[154:157], v[146:149], v[16:31]
	ds_read_b128 v[146:149], v133 offset:49152
	v_mfma_f32_32x32x16_bf16 v[0:15], v[154:157], v[150:153], v[0:15]
	ds_read_b128 v[142:145], v129 offset:32768
	ds_read_b128 v[150:153], v133 offset:53248
	ds_read_b128 v[154:157], v129 offset:36864
	s_waitcnt lgkmcnt(2)
	v_mfma_f32_32x32x16_bf16 v[48:63], v[142:145], v[146:149], v[48:63]
	s_waitcnt lgkmcnt(1)
	v_mfma_f32_32x32x16_bf16 v[32:47], v[142:145], v[150:153], v[32:47]
	s_waitcnt lgkmcnt(0)
	v_mfma_f32_32x32x16_bf16 v[16:31], v[154:157], v[146:149], v[16:31]
	ds_read_b128 v[146:149], v228 offset:49152
	v_mfma_f32_32x32x16_bf16 v[0:15], v[154:157], v[150:153], v[0:15]
	ds_read_b128 v[142:145], v130 offset:32768
	ds_read_b128 v[150:153], v228 offset:53248
	ds_read_b128 v[154:157], v130 offset:36864
	s_waitcnt lgkmcnt(2)
	v_mfma_f32_32x32x16_bf16 v[48:63], v[142:145], v[146:149], v[48:63]
	s_waitcnt lgkmcnt(1)
	v_mfma_f32_32x32x16_bf16 v[32:47], v[142:145], v[150:153], v[32:47]
	s_waitcnt lgkmcnt(0)
	v_mfma_f32_32x32x16_bf16 v[16:31], v[154:157], v[146:149], v[16:31]
	ds_read_b128 v[146:149], v229 offset:49152
	v_mfma_f32_32x32x16_bf16 v[0:15], v[154:157], v[150:153], v[0:15]
	ds_read_b128 v[142:145], v131 offset:32768
	ds_read_b128 v[150:153], v229 offset:53248
	ds_read_b128 v[154:157], v131 offset:36864
	s_waitcnt lgkmcnt(2)
	v_mfma_f32_32x32x16_bf16 v[48:63], v[142:145], v[146:149], v[48:63]
	s_waitcnt lgkmcnt(1)
	v_mfma_f32_32x32x16_bf16 v[32:47], v[142:145], v[150:153], v[32:47]
	s_waitcnt lgkmcnt(0)
	v_mfma_f32_32x32x16_bf16 v[16:31], v[154:157], v[146:149], v[16:31]
	v_mfma_f32_32x32x16_bf16 v[0:15], v[154:157], v[150:153], v[0:15]
	s_waitcnt vmcnt(12)
	ds_write_b128 v134, v[80:83] offset:16384
	ds_write_b128 v134, v[84:87] offset:20480
	ds_write_b128 v134, v[88:91] offset:24576
	ds_write_b128 v134, v[92:95] offset:28672
	s_waitcnt lgkmcnt(0)
	s_barrier
	ds_read_b128 v[142:145], v128
	ds_read_b128 v[146:149], v132 offset:16384
	ds_read_b128 v[150:153], v132 offset:20480
	ds_read_b128 v[154:157], v128 offset:4096
	s_waitcnt lgkmcnt(2)
	v_mfma_f32_32x32x16_bf16 v[48:63], v[142:145], v[146:149], v[48:63]
	s_waitcnt lgkmcnt(1)
	v_mfma_f32_32x32x16_bf16 v[32:47], v[142:145], v[150:153], v[32:47]
	s_waitcnt lgkmcnt(0)
	v_mfma_f32_32x32x16_bf16 v[16:31], v[154:157], v[146:149], v[16:31]
	ds_read_b128 v[146:149], v133 offset:16384
	v_mfma_f32_32x32x16_bf16 v[0:15], v[154:157], v[150:153], v[0:15]
	ds_read_b128 v[142:145], v129
	ds_read_b128 v[150:153], v133 offset:20480
	ds_read_b128 v[154:157], v129 offset:4096
	s_waitcnt lgkmcnt(2)
	v_mfma_f32_32x32x16_bf16 v[48:63], v[142:145], v[146:149], v[48:63]
	s_waitcnt lgkmcnt(1)
	v_mfma_f32_32x32x16_bf16 v[32:47], v[142:145], v[150:153], v[32:47]
	s_waitcnt lgkmcnt(0)
	v_mfma_f32_32x32x16_bf16 v[16:31], v[154:157], v[146:149], v[16:31]
	ds_read_b128 v[146:149], v228 offset:16384
	v_mfma_f32_32x32x16_bf16 v[0:15], v[154:157], v[150:153], v[0:15]
	ds_read_b128 v[142:145], v130
	ds_read_b128 v[150:153], v228 offset:20480
	ds_read_b128 v[154:157], v130 offset:4096
	s_waitcnt lgkmcnt(2)
	v_mfma_f32_32x32x16_bf16 v[48:63], v[142:145], v[146:149], v[48:63]
	s_waitcnt lgkmcnt(1)
	v_mfma_f32_32x32x16_bf16 v[32:47], v[142:145], v[150:153], v[32:47]
	s_waitcnt lgkmcnt(0)
	v_mfma_f32_32x32x16_bf16 v[16:31], v[154:157], v[146:149], v[16:31]
	ds_read_b128 v[146:149], v229 offset:16384
	v_mfma_f32_32x32x16_bf16 v[0:15], v[154:157], v[150:153], v[0:15]
	ds_read_b128 v[142:145], v131
	ds_read_b128 v[150:153], v229 offset:20480
	ds_read_b128 v[154:157], v131 offset:4096
	s_waitcnt lgkmcnt(2)
	v_mfma_f32_32x32x16_bf16 v[48:63], v[142:145], v[146:149], v[48:63]
	s_waitcnt lgkmcnt(1)
	v_mfma_f32_32x32x16_bf16 v[32:47], v[142:145], v[150:153], v[32:47]
	s_waitcnt lgkmcnt(0)
	v_mfma_f32_32x32x16_bf16 v[16:31], v[154:157], v[146:149], v[16:31]
	v_mfma_f32_32x32x16_bf16 v[0:15], v[154:157], v[150:153], v[0:15]
	s_waitcnt vmcnt(8)
	ds_write_b128 v134, v[112:115] offset:49152
	ds_write_b128 v134, v[116:119] offset:53248
	ds_write_b128 v134, v[120:123] offset:57344
	ds_write_b128 v134, v[124:127] offset:61440
	s_waitcnt lgkmcnt(0)
	s_barrier
	ds_read_b128 v[142:145], v128 offset:32768
	ds_read_b128 v[146:149], v132 offset:49152
	ds_read_b128 v[150:153], v132 offset:53248
	ds_read_b128 v[154:157], v128 offset:36864
	s_waitcnt lgkmcnt(2)
	v_mfma_f32_32x32x16_bf16 v[48:63], v[142:145], v[146:149], v[48:63]
	s_waitcnt lgkmcnt(1)
	v_mfma_f32_32x32x16_bf16 v[32:47], v[142:145], v[150:153], v[32:47]
	s_waitcnt lgkmcnt(0)
	v_mfma_f32_32x32x16_bf16 v[16:31], v[154:157], v[146:149], v[16:31]
	ds_read_b128 v[146:149], v133 offset:49152
	v_mfma_f32_32x32x16_bf16 v[0:15], v[154:157], v[150:153], v[0:15]
	ds_read_b128 v[142:145], v129 offset:32768
	ds_read_b128 v[150:153], v133 offset:53248
	ds_read_b128 v[154:157], v129 offset:36864
	s_waitcnt lgkmcnt(2)
	v_mfma_f32_32x32x16_bf16 v[48:63], v[142:145], v[146:149], v[48:63]
	s_waitcnt lgkmcnt(1)
	v_mfma_f32_32x32x16_bf16 v[32:47], v[142:145], v[150:153], v[32:47]
	s_waitcnt lgkmcnt(0)
	v_mfma_f32_32x32x16_bf16 v[16:31], v[154:157], v[146:149], v[16:31]
	ds_read_b128 v[146:149], v228 offset:49152
	v_mfma_f32_32x32x16_bf16 v[0:15], v[154:157], v[150:153], v[0:15]
	ds_read_b128 v[142:145], v130 offset:32768
	ds_read_b128 v[150:153], v228 offset:53248
	ds_read_b128 v[154:157], v130 offset:36864
	s_waitcnt lgkmcnt(2)
	v_mfma_f32_32x32x16_bf16 v[48:63], v[142:145], v[146:149], v[48:63]
	s_waitcnt lgkmcnt(1)
	v_mfma_f32_32x32x16_bf16 v[32:47], v[142:145], v[150:153], v[32:47]
	s_waitcnt lgkmcnt(0)
	v_mfma_f32_32x32x16_bf16 v[16:31], v[154:157], v[146:149], v[16:31]
	ds_read_b128 v[146:149], v229 offset:49152
	v_mfma_f32_32x32x16_bf16 v[0:15], v[154:157], v[150:153], v[0:15]
	ds_read_b128 v[142:145], v131 offset:32768
	ds_read_b128 v[150:153], v229 offset:53248
	ds_read_b128 v[154:157], v131 offset:36864
	s_waitcnt lgkmcnt(2)
	v_mfma_f32_32x32x16_bf16 v[48:63], v[142:145], v[146:149], v[48:63]
	s_waitcnt lgkmcnt(1)
	v_mfma_f32_32x32x16_bf16 v[32:47], v[142:145], v[150:153], v[32:47]
	s_waitcnt lgkmcnt(0)
	v_mfma_f32_32x32x16_bf16 v[16:31], v[154:157], v[146:149], v[16:31]
	v_mfma_f32_32x32x16_bf16 v[0:15], v[154:157], v[150:153], v[0:15]
	s_waitcnt vmcnt(4)
	ds_write_b128 v134, v[176:179] offset:16384
	ds_write_b128 v134, v[180:183] offset:20480
	ds_write_b128 v134, v[184:187] offset:24576
	ds_write_b128 v134, v[188:191] offset:28672
	s_waitcnt lgkmcnt(0)
	s_barrier
	ds_read_b128 v[142:145], v128
	ds_read_b128 v[146:149], v132 offset:16384
	ds_read_b128 v[150:153], v132 offset:20480
	ds_read_b128 v[154:157], v128 offset:4096
	s_waitcnt lgkmcnt(2)
	v_mfma_f32_32x32x16_bf16 v[48:63], v[142:145], v[146:149], v[48:63]
	s_waitcnt lgkmcnt(1)
	v_mfma_f32_32x32x16_bf16 v[32:47], v[142:145], v[150:153], v[32:47]
	s_waitcnt lgkmcnt(0)
	v_mfma_f32_32x32x16_bf16 v[16:31], v[154:157], v[146:149], v[16:31]
	ds_read_b128 v[146:149], v133 offset:16384
	v_mfma_f32_32x32x16_bf16 v[0:15], v[154:157], v[150:153], v[0:15]
	ds_read_b128 v[142:145], v129
	ds_read_b128 v[150:153], v133 offset:20480
	ds_read_b128 v[154:157], v129 offset:4096
	s_waitcnt lgkmcnt(2)
	v_mfma_f32_32x32x16_bf16 v[48:63], v[142:145], v[146:149], v[48:63]
	s_waitcnt lgkmcnt(1)
	v_mfma_f32_32x32x16_bf16 v[32:47], v[142:145], v[150:153], v[32:47]
	s_waitcnt lgkmcnt(0)
	v_mfma_f32_32x32x16_bf16 v[16:31], v[154:157], v[146:149], v[16:31]
	ds_read_b128 v[146:149], v228 offset:16384
	v_mfma_f32_32x32x16_bf16 v[0:15], v[154:157], v[150:153], v[0:15]
	ds_read_b128 v[142:145], v130
	ds_read_b128 v[150:153], v228 offset:20480
	ds_read_b128 v[154:157], v130 offset:4096
	s_waitcnt lgkmcnt(2)
	v_mfma_f32_32x32x16_bf16 v[48:63], v[142:145], v[146:149], v[48:63]
	s_waitcnt lgkmcnt(1)
	v_mfma_f32_32x32x16_bf16 v[32:47], v[142:145], v[150:153], v[32:47]
	s_waitcnt lgkmcnt(0)
	v_mfma_f32_32x32x16_bf16 v[16:31], v[154:157], v[146:149], v[16:31]
	ds_read_b128 v[146:149], v229 offset:16384
	v_mfma_f32_32x32x16_bf16 v[0:15], v[154:157], v[150:153], v[0:15]
	ds_read_b128 v[142:145], v131
	ds_read_b128 v[150:153], v229 offset:20480
	ds_read_b128 v[154:157], v131 offset:4096
	s_waitcnt lgkmcnt(2)
	v_mfma_f32_32x32x16_bf16 v[48:63], v[142:145], v[146:149], v[48:63]
	s_waitcnt lgkmcnt(1)
	v_mfma_f32_32x32x16_bf16 v[32:47], v[142:145], v[150:153], v[32:47]
	s_waitcnt lgkmcnt(0)
	v_mfma_f32_32x32x16_bf16 v[16:31], v[154:157], v[146:149], v[16:31]
	v_mfma_f32_32x32x16_bf16 v[0:15], v[154:157], v[150:153], v[0:15]
	s_waitcnt vmcnt(0)
	ds_write_b128 v134, v[212:215] offset:49152
	ds_write_b128 v134, v[216:219] offset:53248
	ds_write_b128 v134, v[220:223] offset:57344
	ds_write_b128 v134, v[224:227] offset:61440
	s_waitcnt lgkmcnt(0)
	s_barrier
	ds_read_b128 v[142:145], v128 offset:32768
	ds_read_b128 v[146:149], v132 offset:49152
	ds_read_b128 v[150:153], v132 offset:53248
	ds_read_b128 v[154:157], v128 offset:36864
	s_waitcnt lgkmcnt(2)
	v_mfma_f32_32x32x16_bf16 v[48:63], v[142:145], v[146:149], v[48:63]
	s_waitcnt lgkmcnt(1)
	v_mfma_f32_32x32x16_bf16 v[32:47], v[142:145], v[150:153], v[32:47]
	s_waitcnt lgkmcnt(0)
	v_mfma_f32_32x32x16_bf16 v[16:31], v[154:157], v[146:149], v[16:31]
	ds_read_b128 v[146:149], v133 offset:49152
	v_mfma_f32_32x32x16_bf16 v[0:15], v[154:157], v[150:153], v[0:15]
	ds_read_b128 v[142:145], v129 offset:32768
	ds_read_b128 v[150:153], v133 offset:53248
	ds_read_b128 v[154:157], v129 offset:36864
	s_waitcnt lgkmcnt(2)
	v_mfma_f32_32x32x16_bf16 v[48:63], v[142:145], v[146:149], v[48:63]
	s_waitcnt lgkmcnt(1)
	v_mfma_f32_32x32x16_bf16 v[32:47], v[142:145], v[150:153], v[32:47]
	s_waitcnt lgkmcnt(0)
	v_mfma_f32_32x32x16_bf16 v[16:31], v[154:157], v[146:149], v[16:31]
	ds_read_b128 v[146:149], v228 offset:49152
	v_mfma_f32_32x32x16_bf16 v[0:15], v[154:157], v[150:153], v[0:15]
	ds_read_b128 v[142:145], v130 offset:32768
	ds_read_b128 v[150:153], v228 offset:53248
	ds_read_b128 v[154:157], v130 offset:36864
	s_waitcnt lgkmcnt(2)
	v_mfma_f32_32x32x16_bf16 v[48:63], v[142:145], v[146:149], v[48:63]
	s_waitcnt lgkmcnt(1)
	v_mfma_f32_32x32x16_bf16 v[32:47], v[142:145], v[150:153], v[32:47]
	s_waitcnt lgkmcnt(0)
	v_mfma_f32_32x32x16_bf16 v[16:31], v[154:157], v[146:149], v[16:31]
	ds_read_b128 v[146:149], v229 offset:49152
	v_mfma_f32_32x32x16_bf16 v[0:15], v[154:157], v[150:153], v[0:15]
	ds_read_b128 v[142:145], v131 offset:32768
	ds_read_b128 v[150:153], v229 offset:53248
	ds_read_b128 v[154:157], v131 offset:36864
	s_waitcnt lgkmcnt(2)
	v_mfma_f32_32x32x16_bf16 v[48:63], v[142:145], v[146:149], v[48:63]
	s_waitcnt lgkmcnt(1)
	v_mfma_f32_32x32x16_bf16 v[32:47], v[142:145], v[150:153], v[32:47]
	s_waitcnt lgkmcnt(0)
	v_mfma_f32_32x32x16_bf16 v[16:31], v[154:157], v[146:149], v[16:31]
	v_mfma_f32_32x32x16_bf16 v[0:15], v[154:157], v[150:153], v[0:15]
	s_barrier

.LBB0_763:
	v_readlane_b32 s1, v255, 17
	v_readfirstlane_b32 s0, v234
	s_mul_i32 s1, s39, s1
	v_readlane_b32 s8, v255, 19
	s_lshr_b32 s0, s0, 8
	s_add_i32 s10, s1, s8
	s_add_i32 s10, s10, s0
	s_cmp_gt_u32 s10, 47
	s_mov_b64 s[0:1], -1
	s_cbranch_scc1 .LBB0_762
	s_and_b32 s40, s10, 0xff
	s_mul_i32 s0, s40, 0xab
	s_lshr_b32 s41, s0, 11
	s_mul_i32 s0, s41, 12
	s_sub_i32 s0, s10, s0
	s_and_b32 s0, s0, 0xff
	v_readlane_b32 s1, v255, 36
	s_add_i32 s0, s1, s0
	v_mov_b32_e32 v48, v235
	s_lshl_b32 s0, s0, 17
	s_add_u32 s0, s60, s0
	v_ashrrev_i32_e32 v32, 3, v48
	v_ashrrev_i32_e32 v33, 31, v32
	s_addc_u32 s1, s61, 0
	s_mov_b64 s[24:25], s[0:1]
	s_lshl_b32 s10, s41, 17
	v_lshlrev_b64 v[34:35], 10, v[32:33]
	v_lshlrev_b32_e32 v33, 4, v48
	s_add_u32 s44, s37, s10
	v_lshl_add_u64 v[0:1], s[0:1], 0, v[34:35]
	v_and_b32_e32 v192, 0x70, v33
	v_lshlrev_b32_e32 v230, 10, v32
	v_or_b32_e32 v230, v230, v192
	s_addc_u32 s45, s38, 0
	s_mov_b64 s[72:73], s[44:45]
	v_lshl_add_u64 v[128:129], v[0:1], 0, v[192:193]
	v_lshl_add_u64 v[0:1], s[44:45], 0, v[34:35]
	v_add_co_u32_e32 v36, vcc, s88, v128
	v_lshl_add_u64 v[130:131], v[0:1], 0, v[192:193]
	s_nop 0
	v_addc_co_u32_e32 v37, vcc, 0, v129, vcc
	v_add_co_u32_e32 v38, vcc, s88, v130
	v_addc_co_u32_e32 v39, vcc, 0, v131, vcc
	v_add_co_u32_e32 v40, vcc, s97, v128
	s_nop 0
	v_addc_co_u32_e32 v41, vcc, 0, v129, vcc
	v_add_co_u32_e32 v42, vcc, s97, v130
	s_nop 0
	v_addc_co_u32_e32 v43, vcc, 0, v131, vcc
	v_add_co_u32_e32 v44, vcc, s76, v128
	s_nop 0
	v_addc_co_u32_e32 v45, vcc, 0, v129, vcc
	v_add_co_u32_e32 v46, vcc, s76, v130
	s_nop 0
	v_addc_co_u32_e32 v47, vcc, 0, v131, vcc
	v_and_b32_e32 v49, 31, v48
	v_lshrrev_b32_e32 v52, 1, v48
	s_mov_b32 s0, 0x1ffffc0
	v_lshrrev_b32_e32 v50, 5, v48
	v_bfe_u32 v51, v48, 5, 1
	v_bfe_u32 v53, v48, 1, 3
	v_lshlrev_b32_e32 v54, 7, v48
	v_lshlrev_b32_e32 v32, 7, v32
	v_xor_b32_e32 v33, v33, v48
	v_and_or_b32 v48, v52, s0, v49
	s_movk_i32 s0, 0x70
	v_and_b32_e32 v49, 0x2f80, v54
	v_and_or_b32 v54, v33, s0, v32
	v_add_u32_e32 v138, s36, v54
	v_bitop3_b32 v50, v50, v53, 1 bitop3:0x6c
	v_bitop3_b32 v52, v51, v53, 2 bitop3:0x36
	v_lshl_add_u64 v[32:33], s[60:61], 0, v[34:35]
	s_mov_b32 s43, 0
	v_lshl_add_u32 v134, v48, 7, s36
	v_add_u32_e32 v135, s36, v49
	v_lshlrev_b32_e32 v136, 4, v50
	v_lshlrev_b32_e32 v137, 4, v52
	v_lshl_add_u64 v[132:133], v[32:33], 0, v[192:193]
	v_bitop3_b32 v0, v51, v53, 4 bitop3:0x36
	v_lshlrev_b32_e32 v139, 4, v0
	v_bitop3_b32 v0, v51, v53, 6 bitop3:0x36
	v_lshlrev_b32_e32 v140, 4, v0
	s_add_u32 s30, s24, 0x8000
	s_addc_u32 s31, s25, 0
	s_add_u32 s50, s24, 0x10000
	s_addc_u32 s51, s25, 0
	s_add_u32 s54, s24, 0x18000
	s_addc_u32 s55, s25, 0
	s_add_u32 s74, s72, 0x8000
	s_addc_u32 s75, s73, 0
	s_add_u32 s80, s72, 0x10000
	s_addc_u32 s81, s73, 0
	s_add_u32 s86, s72, 0x18000
	s_addc_u32 s87, s73, 0
	s_cmp_lg_u32 s36, 0
	s_cbranch_scc1 .Lsha_glu_h1
	global_load_dwordx4 v[64:67], v230, s[24:25]
	global_load_dwordx4 v[68:71], v230, s[30:31]
	global_load_dwordx4 v[72:75], v230, s[50:51]
	global_load_dwordx4 v[76:79], v230, s[54:55]
	global_load_dwordx4 v[80:83], v230, s[72:73]
	global_load_dwordx4 v[84:87], v230, s[74:75]
	global_load_dwordx4 v[88:91], v230, s[80:81]
	global_load_dwordx4 v[92:95], v230, s[86:87]
	global_load_dwordx4 v[96:99], v230, s[24:25] offset:128
	global_load_dwordx4 v[100:103], v230, s[30:31] offset:128
	global_load_dwordx4 v[104:107], v230, s[50:51] offset:128
	global_load_dwordx4 v[108:111], v230, s[54:55] offset:128
	global_load_dwordx4 v[112:115], v230, s[72:73] offset:128
	global_load_dwordx4 v[116:119], v230, s[74:75] offset:128
	global_load_dwordx4 v[120:123], v230, s[80:81] offset:128
	global_load_dwordx4 v[124:127], v230, s[86:87] offset:128
	global_load_dwordx4 v[160:163], v230, s[24:25] offset:256
	global_load_dwordx4 v[164:167], v230, s[30:31] offset:256
	global_load_dwordx4 v[168:171], v230, s[50:51] offset:256
	global_load_dwordx4 v[172:175], v230, s[54:55] offset:256
	global_load_dwordx4 v[176:179], v230, s[72:73] offset:256
	global_load_dwordx4 v[180:183], v230, s[74:75] offset:256
	global_load_dwordx4 v[184:187], v230, s[80:81] offset:256
	global_load_dwordx4 v[188:191], v230, s[86:87] offset:256
	global_load_dwordx4 v[196:199], v230, s[24:25] offset:384
	global_load_dwordx4 v[200:203], v230, s[30:31] offset:384
	global_load_dwordx4 v[204:207], v230, s[50:51] offset:384
	global_load_dwordx4 v[208:211], v230, s[54:55] offset:384
	global_load_dwordx4 v[212:215], v230, s[72:73] offset:384
	global_load_dwordx4 v[216:219], v230, s[74:75] offset:384
	global_load_dwordx4 v[220:223], v230, s[80:81] offset:384
	global_load_dwordx4 v[224:227], v230, s[86:87] offset:384
	v_add_u32_e32 v128, v134, v136
	v_add_u32_e32 v132, v135, v136
	v_add_u32_e32 v129, v134, v137
	v_add_u32_e32 v133, v135, v137
	v_add_u32_e32 v130, v134, v139
	v_add_u32_e32 v228, v135, v139
	v_add_u32_e32 v131, v134, v140
	v_add_u32_e32 v229, v135, v140
	v_mov_b32_e32 v0, 0
	v_mov_b32_e32 v1, v0
	v_mov_b32_e32 v2, v0
	v_mov_b32_e32 v3, v0
	v_mov_b32_e32 v4, v0
	v_mov_b32_e32 v5, v0
	v_mov_b32_e32 v6, v0
	v_mov_b32_e32 v7, v0
	v_mov_b32_e32 v8, v0
	v_mov_b32_e32 v9, v0
	v_mov_b32_e32 v10, v0
	v_mov_b32_e32 v11, v0
	v_mov_b32_e32 v12, v0
	v_mov_b32_e32 v13, v0
	v_mov_b32_e32 v14, v0
	v_mov_b32_e32 v15, v0
	v_mov_b32_e32 v16, v0
	v_mov_b32_e32 v17, v0
	v_mov_b32_e32 v18, v0
	v_mov_b32_e32 v19, v0
	v_mov_b32_e32 v20, v0
	v_mov_b32_e32 v21, v0
	v_mov_b32_e32 v22, v0
	v_mov_b32_e32 v23, v0
	v_mov_b32_e32 v24, v0
	v_mov_b32_e32 v25, v0
	v_mov_b32_e32 v26, v0
	v_mov_b32_e32 v27, v0
	v_mov_b32_e32 v28, v0
	v_mov_b32_e32 v29, v0
	v_mov_b32_e32 v30, v0
	v_mov_b32_e32 v31, v0
	v_mov_b32_e32 v32, v0
	v_mov_b32_e32 v33, v0
	v_mov_b32_e32 v34, v0
	v_mov_b32_e32 v35, v0
	v_mov_b32_e32 v36, v0
	v_mov_b32_e32 v37, v0
	v_mov_b32_e32 v38, v0
	v_mov_b32_e32 v39, v0
	v_mov_b32_e32 v40, v0
	v_mov_b32_e32 v41, v0
	v_mov_b32_e32 v42, v0
	v_mov_b32_e32 v43, v0
	v_mov_b32_e32 v44, v0
	v_mov_b32_e32 v45, v0
	v_mov_b32_e32 v46, v0
	v_mov_b32_e32 v47, v0
	v_mov_b32_e32 v48, v0
	v_mov_b32_e32 v49, v0
	v_mov_b32_e32 v50, v0
	v_mov_b32_e32 v51, v0
	v_mov_b32_e32 v52, v0
	v_mov_b32_e32 v53, v0
	v_mov_b32_e32 v54, v0
	v_mov_b32_e32 v55, v0
	v_mov_b32_e32 v56, v0
	v_mov_b32_e32 v57, v0
	v_mov_b32_e32 v58, v0
	v_mov_b32_e32 v59, v0
	v_mov_b32_e32 v60, v0
	v_mov_b32_e32 v61, v0
	v_mov_b32_e32 v62, v0
	v_mov_b32_e32 v63, v0
	s_waitcnt vmcnt(24)
	ds_write_b128 v138, v[64:67]
	ds_write_b128 v138, v[80:83] offset:16384
	ds_write_b128 v138, v[68:71] offset:4096
	ds_write_b128 v138, v[84:87] offset:20480
	ds_write_b128 v138, v[72:75] offset:8192
	ds_write_b128 v138, v[88:91] offset:24576
	ds_write_b128 v138, v[76:79] offset:12288
	ds_write_b128 v138, v[92:95] offset:28672
	s_waitcnt lgkmcnt(0)
	s_barrier
	global_load_dwordx4 v[64:67], v230, s[24:25] offset:512
	global_load_dwordx4 v[68:71], v230, s[30:31] offset:512
	global_load_dwordx4 v[72:75], v230, s[50:51] offset:512
	global_load_dwordx4 v[76:79], v230, s[54:55] offset:512
	global_load_dwordx4 v[80:83], v230, s[72:73] offset:512
	global_load_dwordx4 v[84:87], v230, s[74:75] offset:512
	global_load_dwordx4 v[88:91], v230, s[80:81] offset:512
	global_load_dwordx4 v[92:95], v230, s[86:87] offset:512
	ds_read_b128 v[142:145], v128
	ds_read_b128 v[146:149], v132 offset:16384
	ds_read_b128 v[150:153], v132 offset:20480
	ds_read_b128 v[154:157], v128 offset:4096
	s_waitcnt lgkmcnt(2)
	v_mfma_f32_32x32x16_bf16 v[48:63], v[142:145], v[146:149], v[48:63]
	s_waitcnt lgkmcnt(1)
	v_mfma_f32_32x32x16_bf16 v[32:47], v[142:145], v[150:153], v[32:47]
	s_waitcnt lgkmcnt(0)
	v_mfma_f32_32x32x16_bf16 v[16:31], v[154:157], v[146:149], v[16:31]
	ds_read_b128 v[146:149], v133 offset:16384
	v_mfma_f32_32x32x16_bf16 v[0:15], v[154:157], v[150:153], v[0:15]
	ds_read_b128 v[142:145], v129
	ds_read_b128 v[150:153], v133 offset:20480
	ds_read_b128 v[154:157], v129 offset:4096
	s_waitcnt lgkmcnt(2)
	v_mfma_f32_32x32x16_bf16 v[48:63], v[142:145], v[146:149], v[48:63]
	s_waitcnt lgkmcnt(1)
	v_mfma_f32_32x32x16_bf16 v[32:47], v[142:145], v[150:153], v[32:47]
	s_waitcnt lgkmcnt(0)
	v_mfma_f32_32x32x16_bf16 v[16:31], v[154:157], v[146:149], v[16:31]
	ds_read_b128 v[146:149], v228 offset:16384
	v_mfma_f32_32x32x16_bf16 v[0:15], v[154:157], v[150:153], v[0:15]
	ds_read_b128 v[142:145], v130
	ds_read_b128 v[150:153], v228 offset:20480
	ds_read_b128 v[154:157], v130 offset:4096
	s_waitcnt lgkmcnt(2)
	v_mfma_f32_32x32x16_bf16 v[48:63], v[142:145], v[146:149], v[48:63]
	s_waitcnt lgkmcnt(1)
	v_mfma_f32_32x32x16_bf16 v[32:47], v[142:145], v[150:153], v[32:47]
	s_waitcnt lgkmcnt(0)
	v_mfma_f32_32x32x16_bf16 v[16:31], v[154:157], v[146:149], v[16:31]
	ds_read_b128 v[146:149], v229 offset:16384
	v_mfma_f32_32x32x16_bf16 v[0:15], v[154:157], v[150:153], v[0:15]
	ds_read_b128 v[142:145], v131
	ds_read_b128 v[150:153], v229 offset:20480
	ds_read_b128 v[154:157], v131 offset:4096
	s_waitcnt lgkmcnt(2)
	v_mfma_f32_32x32x16_bf16 v[48:63], v[142:145], v[146:149], v[48:63]
	s_waitcnt lgkmcnt(1)
	v_mfma_f32_32x32x16_bf16 v[32:47], v[142:145], v[150:153], v[32:47]
	s_waitcnt lgkmcnt(0)
	v_mfma_f32_32x32x16_bf16 v[16:31], v[154:157], v[146:149], v[16:31]
	v_mfma_f32_32x32x16_bf16 v[0:15], v[154:157], v[150:153], v[0:15]
	s_waitcnt vmcnt(24)
	ds_write_b128 v138, v[96:99] offset:32768
	ds_write_b128 v138, v[112:115] offset:49152
	ds_write_b128 v138, v[100:103] offset:36864
	ds_write_b128 v138, v[116:119] offset:53248
	ds_write_b128 v138, v[104:107] offset:40960
	ds_write_b128 v138, v[120:123] offset:57344
	ds_write_b128 v138, v[108:111] offset:45056
	ds_write_b128 v138, v[124:127] offset:61440
	s_waitcnt lgkmcnt(0)
	s_barrier
	global_load_dwordx4 v[96:99], v230, s[24:25] offset:640
	global_load_dwordx4 v[100:103], v230, s[30:31] offset:640
	global_load_dwordx4 v[104:107], v230, s[50:51] offset:640
	global_load_dwordx4 v[108:111], v230, s[54:55] offset:640
	global_load_dwordx4 v[112:115], v230, s[72:73] offset:640
	global_load_dwordx4 v[116:119], v230, s[74:75] offset:640
	global_load_dwordx4 v[120:123], v230, s[80:81] offset:640
	global_load_dwordx4 v[124:127], v230, s[86:87] offset:640
	ds_read_b128 v[142:145], v128 offset:32768
	ds_read_b128 v[146:149], v132 offset:49152
	ds_read_b128 v[150:153], v132 offset:53248
	ds_read_b128 v[154:157], v128 offset:36864
	s_waitcnt lgkmcnt(2)
	v_mfma_f32_32x32x16_bf16 v[48:63], v[142:145], v[146:149], v[48:63]
	s_waitcnt lgkmcnt(1)
	v_mfma_f32_32x32x16_bf16 v[32:47], v[142:145], v[150:153], v[32:47]
	s_waitcnt lgkmcnt(0)
	v_mfma_f32_32x32x16_bf16 v[16:31], v[154:157], v[146:149], v[16:31]
	ds_read_b128 v[146:149], v133 offset:49152
	v_mfma_f32_32x32x16_bf16 v[0:15], v[154:157], v[150:153], v[0:15]
	ds_read_b128 v[142:145], v129 offset:32768
	ds_read_b128 v[150:153], v133 offset:53248
	ds_read_b128 v[154:157], v129 offset:36864
	s_waitcnt lgkmcnt(2)
	v_mfma_f32_32x32x16_bf16 v[48:63], v[142:145], v[146:149], v[48:63]
	s_waitcnt lgkmcnt(1)
	v_mfma_f32_32x32x16_bf16 v[32:47], v[142:145], v[150:153], v[32:47]
	s_waitcnt lgkmcnt(0)
	v_mfma_f32_32x32x16_bf16 v[16:31], v[154:157], v[146:149], v[16:31]
	ds_read_b128 v[146:149], v228 offset:49152
	v_mfma_f32_32x32x16_bf16 v[0:15], v[154:157], v[150:153], v[0:15]
	ds_read_b128 v[142:145], v130 offset:32768
	ds_read_b128 v[150:153], v228 offset:53248
	ds_read_b128 v[154:157], v130 offset:36864
	s_waitcnt lgkmcnt(2)
	v_mfma_f32_32x32x16_bf16 v[48:63], v[142:145], v[146:149], v[48:63]
	s_waitcnt lgkmcnt(1)
	v_mfma_f32_32x32x16_bf16 v[32:47], v[142:145], v[150:153], v[32:47]
	s_waitcnt lgkmcnt(0)
	v_mfma_f32_32x32x16_bf16 v[16:31], v[154:157], v[146:149], v[16:31]
	ds_read_b128 v[146:149], v229 offset:49152
	v_mfma_f32_32x32x16_bf16 v[0:15], v[154:157], v[150:153], v[0:15]
	ds_read_b128 v[142:145], v131 offset:32768
	ds_read_b128 v[150:153], v229 offset:53248
	ds_read_b128 v[154:157], v131 offset:36864
	s_waitcnt lgkmcnt(2)
	v_mfma_f32_32x32x16_bf16 v[48:63], v[142:145], v[146:149], v[48:63]
	s_waitcnt lgkmcnt(1)
	v_mfma_f32_32x32x16_bf16 v[32:47], v[142:145], v[150:153], v[32:47]
	s_waitcnt lgkmcnt(0)
	v_mfma_f32_32x32x16_bf16 v[16:31], v[154:157], v[146:149], v[16:31]
	v_mfma_f32_32x32x16_bf16 v[0:15], v[154:157], v[150:153], v[0:15]
	s_waitcnt vmcnt(24)
	ds_write_b128 v138, v[160:163]
	ds_write_b128 v138, v[176:179] offset:16384
	ds_write_b128 v138, v[164:167] offset:4096
	ds_write_b128 v138, v[180:183] offset:20480
	ds_write_b128 v138, v[168:171] offset:8192
	ds_write_b128 v138, v[184:187] offset:24576
	ds_write_b128 v138, v[172:175] offset:12288
	ds_write_b128 v138, v[188:191] offset:28672
	s_waitcnt lgkmcnt(0)
	s_barrier
	global_load_dwordx4 v[160:163], v230, s[24:25] offset:768
	global_load_dwordx4 v[164:167], v230, s[30:31] offset:768
	global_load_dwordx4 v[168:171], v230, s[50:51] offset:768
	global_load_dwordx4 v[172:175], v230, s[54:55] offset:768
	global_load_dwordx4 v[176:179], v230, s[72:73] offset:768
	global_load_dwordx4 v[180:183], v230, s[74:75] offset:768
	global_load_dwordx4 v[184:187], v230, s[80:81] offset:768
	global_load_dwordx4 v[188:191], v230, s[86:87] offset:768
	ds_read_b128 v[142:145], v128
	ds_read_b128 v[146:149], v132 offset:16384
	ds_read_b128 v[150:153], v132 offset:20480
	ds_read_b128 v[154:157], v128 offset:4096
	s_waitcnt lgkmcnt(2)
	v_mfma_f32_32x32x16_bf16 v[48:63], v[142:145], v[146:149], v[48:63]
	s_waitcnt lgkmcnt(1)
	v_mfma_f32_32x32x16_bf16 v[32:47], v[142:145], v[150:153], v[32:47]
	s_waitcnt lgkmcnt(0)
	v_mfma_f32_32x32x16_bf16 v[16:31], v[154:157], v[146:149], v[16:31]
	ds_read_b128 v[146:149], v133 offset:16384
	v_mfma_f32_32x32x16_bf16 v[0:15], v[154:157], v[150:153], v[0:15]
	ds_read_b128 v[142:145], v129
	ds_read_b128 v[150:153], v133 offset:20480
	ds_read_b128 v[154:157], v129 offset:4096
	s_waitcnt lgkmcnt(2)
	v_mfma_f32_32x32x16_bf16 v[48:63], v[142:145], v[146:149], v[48:63]
	s_waitcnt lgkmcnt(1)
	v_mfma_f32_32x32x16_bf16 v[32:47], v[142:145], v[150:153], v[32:47]
	s_waitcnt lgkmcnt(0)
	v_mfma_f32_32x32x16_bf16 v[16:31], v[154:157], v[146:149], v[16:31]
	ds_read_b128 v[146:149], v228 offset:16384
	v_mfma_f32_32x32x16_bf16 v[0:15], v[154:157], v[150:153], v[0:15]
	ds_read_b128 v[142:145], v130
	ds_read_b128 v[150:153], v228 offset:20480
	ds_read_b128 v[154:157], v130 offset:4096
	s_waitcnt lgkmcnt(2)
	v_mfma_f32_32x32x16_bf16 v[48:63], v[142:145], v[146:149], v[48:63]
	s_waitcnt lgkmcnt(1)
	v_mfma_f32_32x32x16_bf16 v[32:47], v[142:145], v[150:153], v[32:47]
	s_waitcnt lgkmcnt(0)
	v_mfma_f32_32x32x16_bf16 v[16:31], v[154:157], v[146:149], v[16:31]
	ds_read_b128 v[146:149], v229 offset:16384
	v_mfma_f32_32x32x16_bf16 v[0:15], v[154:157], v[150:153], v[0:15]
	ds_read_b128 v[142:145], v131
	ds_read_b128 v[150:153], v229 offset:20480
	ds_read_b128 v[154:157], v131 offset:4096
	s_waitcnt lgkmcnt(2)
	v_mfma_f32_32x32x16_bf16 v[48:63], v[142:145], v[146:149], v[48:63]
	s_waitcnt lgkmcnt(1)
	v_mfma_f32_32x32x16_bf16 v[32:47], v[142:145], v[150:153], v[32:47]
	s_waitcnt lgkmcnt(0)
	v_mfma_f32_32x32x16_bf16 v[16:31], v[154:157], v[146:149], v[16:31]
	v_mfma_f32_32x32x16_bf16 v[0:15], v[154:157], v[150:153], v[0:15]
	s_waitcnt vmcnt(24)
	ds_write_b128 v138, v[196:199] offset:32768
	ds_write_b128 v138, v[212:215] offset:49152
	ds_write_b128 v138, v[200:203] offset:36864
	ds_write_b128 v138, v[216:219] offset:53248
	ds_write_b128 v138, v[204:207] offset:40960
	ds_write_b128 v138, v[220:223] offset:57344
	ds_write_b128 v138, v[208:211] offset:45056
	ds_write_b128 v138, v[224:227] offset:61440
	s_waitcnt lgkmcnt(0)
	s_barrier
	global_load_dwordx4 v[196:199], v230, s[24:25] offset:896
	global_load_dwordx4 v[200:203], v230, s[30:31] offset:896
	global_load_dwordx4 v[204:207], v230, s[50:51] offset:896
	global_load_dwordx4 v[208:211], v230, s[54:55] offset:896
	global_load_dwordx4 v[212:215], v230, s[72:73] offset:896
	global_load_dwordx4 v[216:219], v230, s[74:75] offset:896
	global_load_dwordx4 v[220:223], v230, s[80:81] offset:896
	global_load_dwordx4 v[224:227], v230, s[86:87] offset:896
	ds_read_b128 v[142:145], v128 offset:32768
	ds_read_b128 v[146:149], v132 offset:49152
	ds_read_b128 v[150:153], v132 offset:53248
	ds_read_b128 v[154:157], v128 offset:36864
	s_waitcnt lgkmcnt(2)
	v_mfma_f32_32x32x16_bf16 v[48:63], v[142:145], v[146:149], v[48:63]
	s_waitcnt lgkmcnt(1)
	v_mfma_f32_32x32x16_bf16 v[32:47], v[142:145], v[150:153], v[32:47]
	s_waitcnt lgkmcnt(0)
	v_mfma_f32_32x32x16_bf16 v[16:31], v[154:157], v[146:149], v[16:31]
	ds_read_b128 v[146:149], v133 offset:49152
	v_mfma_f32_32x32x16_bf16 v[0:15], v[154:157], v[150:153], v[0:15]
	ds_read_b128 v[142:145], v129 offset:32768
	ds_read_b128 v[150:153], v133 offset:53248
	ds_read_b128 v[154:157], v129 offset:36864
	s_waitcnt lgkmcnt(2)
	v_mfma_f32_32x32x16_bf16 v[48:63], v[142:145], v[146:149], v[48:63]
	s_waitcnt lgkmcnt(1)
	v_mfma_f32_32x32x16_bf16 v[32:47], v[142:145], v[150:153], v[32:47]
	s_waitcnt lgkmcnt(0)
	v_mfma_f32_32x32x16_bf16 v[16:31], v[154:157], v[146:149], v[16:31]
	ds_read_b128 v[146:149], v228 offset:49152
	v_mfma_f32_32x32x16_bf16 v[0:15], v[154:157], v[150:153], v[0:15]
	ds_read_b128 v[142:145], v130 offset:32768
	ds_read_b128 v[150:153], v228 offset:53248
	ds_read_b128 v[154:157], v130 offset:36864
	s_waitcnt lgkmcnt(2)
	v_mfma_f32_32x32x16_bf16 v[48:63], v[142:145], v[146:149], v[48:63]
	s_waitcnt lgkmcnt(1)
	v_mfma_f32_32x32x16_bf16 v[32:47], v[142:145], v[150:153], v[32:47]
	s_waitcnt lgkmcnt(0)
	v_mfma_f32_32x32x16_bf16 v[16:31], v[154:157], v[146:149], v[16:31]
	ds_read_b128 v[146:149], v229 offset:49152
	v_mfma_f32_32x32x16_bf16 v[0:15], v[154:157], v[150:153], v[0:15]
	ds_read_b128 v[142:145], v131 offset:32768
	ds_read_b128 v[150:153], v229 offset:53248
	ds_read_b128 v[154:157], v131 offset:36864
	s_waitcnt lgkmcnt(2)
	v_mfma_f32_32x32x16_bf16 v[48:63], v[142:145], v[146:149], v[48:63]
	s_waitcnt lgkmcnt(1)
	v_mfma_f32_32x32x16_bf16 v[32:47], v[142:145], v[150:153], v[32:47]
	s_waitcnt lgkmcnt(0)
	v_mfma_f32_32x32x16_bf16 v[16:31], v[154:157], v[146:149], v[16:31]
	v_mfma_f32_32x32x16_bf16 v[0:15], v[154:157], v[150:153], v[0:15]
	s_waitcnt vmcnt(24)
	ds_write_b128 v138, v[64:67]
	ds_write_b128 v138, v[80:83] offset:16384
	ds_write_b128 v138, v[68:71] offset:4096
	ds_write_b128 v138, v[84:87] offset:20480
	ds_write_b128 v138, v[72:75] offset:8192
	ds_write_b128 v138, v[88:91] offset:24576
	ds_write_b128 v138, v[76:79] offset:12288
	ds_write_b128 v138, v[92:95] offset:28672
	s_waitcnt lgkmcnt(0)
	s_barrier
	ds_read_b128 v[142:145], v128
	ds_read_b128 v[146:149], v132 offset:16384
	ds_read_b128 v[150:153], v132 offset:20480
	ds_read_b128 v[154:157], v128 offset:4096
	s_waitcnt lgkmcnt(2)
	v_mfma_f32_32x32x16_bf16 v[48:63], v[142:145], v[146:149], v[48:63]
	s_waitcnt lgkmcnt(1)
	v_mfma_f32_32x32x16_bf16 v[32:47], v[142:145], v[150:153], v[32:47]
	s_waitcnt lgkmcnt(0)
	v_mfma_f32_32x32x16_bf16 v[16:31], v[154:157], v[146:149], v[16:31]
	ds_read_b128 v[146:149], v133 offset:16384
	v_mfma_f32_32x32x16_bf16 v[0:15], v[154:157], v[150:153], v[0:15]
	ds_read_b128 v[142:145], v129
	ds_read_b128 v[150:153], v133 offset:20480
	ds_read_b128 v[154:157], v129 offset:4096
	s_waitcnt lgkmcnt(2)
	v_mfma_f32_32x32x16_bf16 v[48:63], v[142:145], v[146:149], v[48:63]
	s_waitcnt lgkmcnt(1)
	v_mfma_f32_32x32x16_bf16 v[32:47], v[142:145], v[150:153], v[32:47]
	s_waitcnt lgkmcnt(0)
	v_mfma_f32_32x32x16_bf16 v[16:31], v[154:157], v[146:149], v[16:31]
	ds_read_b128 v[146:149], v228 offset:16384
	v_mfma_f32_32x32x16_bf16 v[0:15], v[154:157], v[150:153], v[0:15]
	ds_read_b128 v[142:145], v130
	ds_read_b128 v[150:153], v228 offset:20480
	ds_read_b128 v[154:157], v130 offset:4096
	s_waitcnt lgkmcnt(2)
	v_mfma_f32_32x32x16_bf16 v[48:63], v[142:145], v[146:149], v[48:63]
	s_waitcnt lgkmcnt(1)
	v_mfma_f32_32x32x16_bf16 v[32:47], v[142:145], v[150:153], v[32:47]
	s_waitcnt lgkmcnt(0)
	v_mfma_f32_32x32x16_bf16 v[16:31], v[154:157], v[146:149], v[16:31]
	ds_read_b128 v[146:149], v229 offset:16384
	v_mfma_f32_32x32x16_bf16 v[0:15], v[154:157], v[150:153], v[0:15]
	ds_read_b128 v[142:145], v131
	ds_read_b128 v[150:153], v229 offset:20480
	ds_read_b128 v[154:157], v131 offset:4096
	s_waitcnt lgkmcnt(2)
	v_mfma_f32_32x32x16_bf16 v[48:63], v[142:145], v[146:149], v[48:63]
	s_waitcnt lgkmcnt(1)
	v_mfma_f32_32x32x16_bf16 v[32:47], v[142:145], v[150:153], v[32:47]
	s_waitcnt lgkmcnt(0)
	v_mfma_f32_32x32x16_bf16 v[16:31], v[154:157], v[146:149], v[16:31]
	v_mfma_f32_32x32x16_bf16 v[0:15], v[154:157], v[150:153], v[0:15]
	s_waitcnt vmcnt(16)
	ds_write_b128 v138, v[96:99] offset:32768
	ds_write_b128 v138, v[112:115] offset:49152
	ds_write_b128 v138, v[100:103] offset:36864
	ds_write_b128 v138, v[116:119] offset:53248
	ds_write_b128 v138, v[104:107] offset:40960
	ds_write_b128 v138, v[120:123] offset:57344
	ds_write_b128 v138, v[108:111] offset:45056
	ds_write_b128 v138, v[124:127] offset:61440
	s_waitcnt lgkmcnt(0)
	s_barrier
	ds_read_b128 v[142:145], v128 offset:32768
	ds_read_b128 v[146:149], v132 offset:49152
	ds_read_b128 v[150:153], v132 offset:53248
	ds_read_b128 v[154:157], v128 offset:36864
	s_waitcnt lgkmcnt(2)
	v_mfma_f32_32x32x16_bf16 v[48:63], v[142:145], v[146:149], v[48:63]
	s_waitcnt lgkmcnt(1)
	v_mfma_f32_32x32x16_bf16 v[32:47], v[142:145], v[150:153], v[32:47]
	s_waitcnt lgkmcnt(0)
	v_mfma_f32_32x32x16_bf16 v[16:31], v[154:157], v[146:149], v[16:31]
	ds_read_b128 v[146:149], v133 offset:49152
	v_mfma_f32_32x32x16_bf16 v[0:15], v[154:157], v[150:153], v[0:15]
	ds_read_b128 v[142:145], v129 offset:32768
	ds_read_b128 v[150:153], v133 offset:53248
	ds_read_b128 v[154:157], v129 offset:36864
	s_waitcnt lgkmcnt(2)
	v_mfma_f32_32x32x16_bf16 v[48:63], v[142:145], v[146:149], v[48:63]
	s_waitcnt lgkmcnt(1)
	v_mfma_f32_32x32x16_bf16 v[32:47], v[142:145], v[150:153], v[32:47]
	s_waitcnt lgkmcnt(0)
	v_mfma_f32_32x32x16_bf16 v[16:31], v[154:157], v[146:149], v[16:31]
	ds_read_b128 v[146:149], v228 offset:49152
	v_mfma_f32_32x32x16_bf16 v[0:15], v[154:157], v[150:153], v[0:15]
	ds_read_b128 v[142:145], v130 offset:32768
	ds_read_b128 v[150:153], v228 offset:53248
	ds_read_b128 v[154:157], v130 offset:36864
	s_waitcnt lgkmcnt(2)
	v_mfma_f32_32x32x16_bf16 v[48:63], v[142:145], v[146:149], v[48:63]
	s_waitcnt lgkmcnt(1)
	v_mfma_f32_32x32x16_bf16 v[32:47], v[142:145], v[150:153], v[32:47]
	s_waitcnt lgkmcnt(0)
	v_mfma_f32_32x32x16_bf16 v[16:31], v[154:157], v[146:149], v[16:31]
	ds_read_b128 v[146:149], v229 offset:49152
	v_mfma_f32_32x32x16_bf16 v[0:15], v[154:157], v[150:153], v[0:15]
	ds_read_b128 v[142:145], v131 offset:32768
	ds_read_b128 v[150:153], v229 offset:53248
	ds_read_b128 v[154:157], v131 offset:36864
	s_waitcnt lgkmcnt(2)
	v_mfma_f32_32x32x16_bf16 v[48:63], v[142:145], v[146:149], v[48:63]
	s_waitcnt lgkmcnt(1)
	v_mfma_f32_32x32x16_bf16 v[32:47], v[142:145], v[150:153], v[32:47]
	s_waitcnt lgkmcnt(0)
	v_mfma_f32_32x32x16_bf16 v[16:31], v[154:157], v[146:149], v[16:31]
	v_mfma_f32_32x32x16_bf16 v[0:15], v[154:157], v[150:153], v[0:15]
	s_waitcnt vmcnt(8)
	ds_write_b128 v138, v[160:163]
	ds_write_b128 v138, v[176:179] offset:16384
	ds_write_b128 v138, v[164:167] offset:4096
	ds_write_b128 v138, v[180:183] offset:20480
	ds_write_b128 v138, v[168:171] offset:8192
	ds_write_b128 v138, v[184:187] offset:24576
	ds_write_b128 v138, v[172:175] offset:12288
	ds_write_b128 v138, v[188:191] offset:28672
	s_waitcnt lgkmcnt(0)
	s_barrier
	ds_read_b128 v[142:145], v128
	ds_read_b128 v[146:149], v132 offset:16384
	ds_read_b128 v[150:153], v132 offset:20480
	ds_read_b128 v[154:157], v128 offset:4096
	s_waitcnt lgkmcnt(2)
	v_mfma_f32_32x32x16_bf16 v[48:63], v[142:145], v[146:149], v[48:63]
	s_waitcnt lgkmcnt(1)
	v_mfma_f32_32x32x16_bf16 v[32:47], v[142:145], v[150:153], v[32:47]
	s_waitcnt lgkmcnt(0)
	v_mfma_f32_32x32x16_bf16 v[16:31], v[154:157], v[146:149], v[16:31]
	ds_read_b128 v[146:149], v133 offset:16384
	v_mfma_f32_32x32x16_bf16 v[0:15], v[154:157], v[150:153], v[0:15]
	ds_read_b128 v[142:145], v129
	ds_read_b128 v[150:153], v133 offset:20480
	ds_read_b128 v[154:157], v129 offset:4096
	s_waitcnt lgkmcnt(2)
	v_mfma_f32_32x32x16_bf16 v[48:63], v[142:145], v[146:149], v[48:63]
	s_waitcnt lgkmcnt(1)
	v_mfma_f32_32x32x16_bf16 v[32:47], v[142:145], v[150:153], v[32:47]
	s_waitcnt lgkmcnt(0)
	v_mfma_f32_32x32x16_bf16 v[16:31], v[154:157], v[146:149], v[16:31]
	ds_read_b128 v[146:149], v228 offset:16384
	v_mfma_f32_32x32x16_bf16 v[0:15], v[154:157], v[150:153], v[0:15]
	ds_read_b128 v[142:145], v130
	ds_read_b128 v[150:153], v228 offset:20480
	ds_read_b128 v[154:157], v130 offset:4096
	s_waitcnt lgkmcnt(2)
	v_mfma_f32_32x32x16_bf16 v[48:63], v[142:145], v[146:149], v[48:63]
	s_waitcnt lgkmcnt(1)
	v_mfma_f32_32x32x16_bf16 v[32:47], v[142:145], v[150:153], v[32:47]
	s_waitcnt lgkmcnt(0)
	v_mfma_f32_32x32x16_bf16 v[16:31], v[154:157], v[146:149], v[16:31]
	ds_read_b128 v[146:149], v229 offset:16384
	v_mfma_f32_32x32x16_bf16 v[0:15], v[154:157], v[150:153], v[0:15]
	ds_read_b128 v[142:145], v131
	ds_read_b128 v[150:153], v229 offset:20480
	ds_read_b128 v[154:157], v131 offset:4096
	s_waitcnt lgkmcnt(2)
	v_mfma_f32_32x32x16_bf16 v[48:63], v[142:145], v[146:149], v[48:63]
	s_waitcnt lgkmcnt(1)
	v_mfma_f32_32x32x16_bf16 v[32:47], v[142:145], v[150:153], v[32:47]
	s_waitcnt lgkmcnt(0)
	v_mfma_f32_32x32x16_bf16 v[16:31], v[154:157], v[146:149], v[16:31]
	v_mfma_f32_32x32x16_bf16 v[0:15], v[154:157], v[150:153], v[0:15]
	s_waitcnt vmcnt(0)
	ds_write_b128 v138, v[196:199] offset:32768
	ds_write_b128 v138, v[212:215] offset:49152
	ds_write_b128 v138, v[200:203] offset:36864
	ds_write_b128 v138, v[216:219] offset:53248
	ds_write_b128 v138, v[204:207] offset:40960
	ds_write_b128 v138, v[220:223] offset:57344
	ds_write_b128 v138, v[208:211] offset:45056
	ds_write_b128 v138, v[224:227] offset:61440
	s_waitcnt lgkmcnt(0)
	s_barrier
	ds_read_b128 v[142:145], v128 offset:32768
	ds_read_b128 v[146:149], v132 offset:49152
	ds_read_b128 v[150:153], v132 offset:53248
	ds_read_b128 v[154:157], v128 offset:36864
	s_waitcnt lgkmcnt(2)
	v_mfma_f32_32x32x16_bf16 v[48:63], v[142:145], v[146:149], v[48:63]
	s_waitcnt lgkmcnt(1)
	v_mfma_f32_32x32x16_bf16 v[32:47], v[142:145], v[150:153], v[32:47]
	s_waitcnt lgkmcnt(0)
	v_mfma_f32_32x32x16_bf16 v[16:31], v[154:157], v[146:149], v[16:31]
	ds_read_b128 v[146:149], v133 offset:49152
	v_mfma_f32_32x32x16_bf16 v[0:15], v[154:157], v[150:153], v[0:15]
	ds_read_b128 v[142:145], v129 offset:32768
	ds_read_b128 v[150:153], v133 offset:53248
	ds_read_b128 v[154:157], v129 offset:36864
	s_waitcnt lgkmcnt(2)
	v_mfma_f32_32x32x16_bf16 v[48:63], v[142:145], v[146:149], v[48:63]
	s_waitcnt lgkmcnt(1)
	v_mfma_f32_32x32x16_bf16 v[32:47], v[142:145], v[150:153], v[32:47]
	s_waitcnt lgkmcnt(0)
	v_mfma_f32_32x32x16_bf16 v[16:31], v[154:157], v[146:149], v[16:31]
	ds_read_b128 v[146:149], v228 offset:49152
	v_mfma_f32_32x32x16_bf16 v[0:15], v[154:157], v[150:153], v[0:15]
	ds_read_b128 v[142:145], v130 offset:32768
	ds_read_b128 v[150:153], v228 offset:53248
	ds_read_b128 v[154:157], v130 offset:36864
	s_waitcnt lgkmcnt(2)
	v_mfma_f32_32x32x16_bf16 v[48:63], v[142:145], v[146:149], v[48:63]
	s_waitcnt lgkmcnt(1)
	v_mfma_f32_32x32x16_bf16 v[32:47], v[142:145], v[150:153], v[32:47]
	s_waitcnt lgkmcnt(0)
	v_mfma_f32_32x32x16_bf16 v[16:31], v[154:157], v[146:149], v[16:31]
	ds_read_b128 v[146:149], v229 offset:49152
	v_mfma_f32_32x32x16_bf16 v[0:15], v[154:157], v[150:153], v[0:15]
	ds_read_b128 v[142:145], v131 offset:32768
	ds_read_b128 v[150:153], v229 offset:53248
	ds_read_b128 v[154:157], v131 offset:36864
	s_waitcnt lgkmcnt(2)
	v_mfma_f32_32x32x16_bf16 v[48:63], v[142:145], v[146:149], v[48:63]
	s_waitcnt lgkmcnt(1)
	v_mfma_f32_32x32x16_bf16 v[32:47], v[142:145], v[150:153], v[32:47]
	s_waitcnt lgkmcnt(0)
	v_mfma_f32_32x32x16_bf16 v[16:31], v[154:157], v[146:149], v[16:31]
	v_mfma_f32_32x32x16_bf16 v[0:15], v[154:157], v[150:153], v[0:15]
	s_barrier
	s_branch .Lsha_glu_j
.Lsha_glu_h1:
	global_load_dwordx4 v[64:67], v230, s[24:25]
	global_load_dwordx4 v[68:71], v230, s[30:31]
	global_load_dwordx4 v[72:75], v230, s[50:51]
	global_load_dwordx4 v[76:79], v230, s[54:55]
	global_load_dwordx4 v[96:99], v230, s[24:25] offset:128
	global_load_dwordx4 v[100:103], v230, s[30:31] offset:128
	global_load_dwordx4 v[104:107], v230, s[50:51] offset:128
	global_load_dwordx4 v[108:111], v230, s[54:55] offset:128
	global_load_dwordx4 v[160:163], v230, s[24:25] offset:256
	global_load_dwordx4 v[164:167], v230, s[30:31] offset:256
	global_load_dwordx4 v[168:171], v230, s[50:51] offset:256
	global_load_dwordx4 v[172:175], v230, s[54:55] offset:256
	global_load_dwordx4 v[196:199], v230, s[24:25] offset:384
	global_load_dwordx4 v[200:203], v230, s[30:31] offset:384
	global_load_dwordx4 v[204:207], v230, s[50:51] offset:384
	global_load_dwordx4 v[208:211], v230, s[54:55] offset:384
	v_add_u32_e32 v128, v134, v136
	v_add_u32_e32 v132, v135, v136
	v_add_u32_e32 v129, v134, v137
	v_add_u32_e32 v133, v135, v137
	v_add_u32_e32 v130, v134, v139
	v_add_u32_e32 v228, v135, v139
	v_add_u32_e32 v131, v134, v140
	v_add_u32_e32 v229, v135, v140
	v_add_u32_e32 v132, 0xffff0000, v132
	v_add_u32_e32 v133, 0xffff0000, v133
	v_add_u32_e32 v228, 0xffff0000, v228
	v_add_u32_e32 v229, 0xffff0000, v229
	v_mov_b32_e32 v0, 0
	v_mov_b32_e32 v1, v0
	v_mov_b32_e32 v2, v0
	v_mov_b32_e32 v3, v0
	v_mov_b32_e32 v4, v0
	v_mov_b32_e32 v5, v0
	v_mov_b32_e32 v6, v0
	v_mov_b32_e32 v7, v0
	v_mov_b32_e32 v8, v0
	v_mov_b32_e32 v9, v0
	v_mov_b32_e32 v10, v0
	v_mov_b32_e32 v11, v0
	v_mov_b32_e32 v12, v0
	v_mov_b32_e32 v13, v0
	v_mov_b32_e32 v14, v0
	v_mov_b32_e32 v15, v0
	v_mov_b32_e32 v16, v0
	v_mov_b32_e32 v17, v0
	v_mov_b32_e32 v18, v0
	v_mov_b32_e32 v19, v0
	v_mov_b32_e32 v20, v0
	v_mov_b32_e32 v21, v0
	v_mov_b32_e32 v22, v0
	v_mov_b32_e32 v23, v0
	v_mov_b32_e32 v24, v0
	v_mov_b32_e32 v25, v0
	v_mov_b32_e32 v26, v0
	v_mov_b32_e32 v27, v0
	v_mov_b32_e32 v28, v0
	v_mov_b32_e32 v29, v0
	v_mov_b32_e32 v30, v0
	v_mov_b32_e32 v31, v0
	v_mov_b32_e32 v32, v0
	v_mov_b32_e32 v33, v0
	v_mov_b32_e32 v34, v0
	v_mov_b32_e32 v35, v0
	v_mov_b32_e32 v36, v0
	v_mov_b32_e32 v37, v0
	v_mov_b32_e32 v38, v0
	v_mov_b32_e32 v39, v0
	v_mov_b32_e32 v40, v0
	v_mov_b32_e32 v41, v0
	v_mov_b32_e32 v42, v0
	v_mov_b32_e32 v43, v0
	v_mov_b32_e32 v44, v0
	v_mov_b32_e32 v45, v0
	v_mov_b32_e32 v46, v0
	v_mov_b32_e32 v47, v0
	v_mov_b32_e32 v48, v0
	v_mov_b32_e32 v49, v0
	v_mov_b32_e32 v50, v0
	v_mov_b32_e32 v51, v0
	v_mov_b32_e32 v52, v0
	v_mov_b32_e32 v53, v0
	v_mov_b32_e32 v54, v0
	v_mov_b32_e32 v55, v0
	v_mov_b32_e32 v56, v0
	v_mov_b32_e32 v57, v0
	v_mov_b32_e32 v58, v0
	v_mov_b32_e32 v59, v0
	v_mov_b32_e32 v60, v0
	v_mov_b32_e32 v61, v0
	v_mov_b32_e32 v62, v0
	v_mov_b32_e32 v63, v0
	s_waitcnt vmcnt(12)
	ds_write_b128 v138, v[64:67]
	ds_write_b128 v138, v[68:71] offset:4096
	ds_write_b128 v138, v[72:75] offset:8192
	ds_write_b128 v138, v[76:79] offset:12288
	s_waitcnt lgkmcnt(0)
	s_barrier
	global_load_dwordx4 v[64:67], v230, s[24:25] offset:512
	global_load_dwordx4 v[68:71], v230, s[30:31] offset:512
	global_load_dwordx4 v[72:75], v230, s[50:51] offset:512
	global_load_dwordx4 v[76:79], v230, s[54:55] offset:512
	ds_read_b128 v[142:145], v128
	ds_read_b128 v[146:149], v132 offset:16384
	ds_read_b128 v[150:153], v132 offset:20480
	ds_read_b128 v[154:157], v128 offset:4096
	s_waitcnt lgkmcnt(2)
	v_mfma_f32_32x32x16_bf16 v[48:63], v[142:145], v[146:149], v[48:63]
	s_waitcnt lgkmcnt(1)
	v_mfma_f32_32x32x16_bf16 v[32:47], v[142:145], v[150:153], v[32:47]
	s_waitcnt lgkmcnt(0)
	v_mfma_f32_32x32x16_bf16 v[16:31], v[154:157], v[146:149], v[16:31]
	ds_read_b128 v[146:149], v133 offset:16384
	v_mfma_f32_32x32x16_bf16 v[0:15], v[154:157], v[150:153], v[0:15]
	ds_read_b128 v[142:145], v129
	ds_read_b128 v[150:153], v133 offset:20480
	ds_read_b128 v[154:157], v129 offset:4096
	s_waitcnt lgkmcnt(2)
	v_mfma_f32_32x32x16_bf16 v[48:63], v[142:145], v[146:149], v[48:63]
	s_waitcnt lgkmcnt(1)
	v_mfma_f32_32x32x16_bf16 v[32:47], v[142:145], v[150:153], v[32:47]
	s_waitcnt lgkmcnt(0)
	v_mfma_f32_32x32x16_bf16 v[16:31], v[154:157], v[146:149], v[16:31]
	ds_read_b128 v[146:149], v228 offset:16384
	v_mfma_f32_32x32x16_bf16 v[0:15], v[154:157], v[150:153], v[0:15]
	ds_read_b128 v[142:145], v130
	ds_read_b128 v[150:153], v228 offset:20480
	ds_read_b128 v[154:157], v130 offset:4096
	s_waitcnt lgkmcnt(2)
	v_mfma_f32_32x32x16_bf16 v[48:63], v[142:145], v[146:149], v[48:63]
	s_waitcnt lgkmcnt(1)
	v_mfma_f32_32x32x16_bf16 v[32:47], v[142:145], v[150:153], v[32:47]
	s_waitcnt lgkmcnt(0)
	v_mfma_f32_32x32x16_bf16 v[16:31], v[154:157], v[146:149], v[16:31]
	ds_read_b128 v[146:149], v229 offset:16384
	v_mfma_f32_32x32x16_bf16 v[0:15], v[154:157], v[150:153], v[0:15]
	ds_read_b128 v[142:145], v131
	ds_read_b128 v[150:153], v229 offset:20480
	ds_read_b128 v[154:157], v131 offset:4096
	s_waitcnt lgkmcnt(2)
	v_mfma_f32_32x32x16_bf16 v[48:63], v[142:145], v[146:149], v[48:63]
	s_waitcnt lgkmcnt(1)
	v_mfma_f32_32x32x16_bf16 v[32:47], v[142:145], v[150:153], v[32:47]
	s_waitcnt lgkmcnt(0)
	v_mfma_f32_32x32x16_bf16 v[16:31], v[154:157], v[146:149], v[16:31]
	v_mfma_f32_32x32x16_bf16 v[0:15], v[154:157], v[150:153], v[0:15]
	s_waitcnt vmcnt(12)
	ds_write_b128 v138, v[96:99] offset:32768
	ds_write_b128 v138, v[100:103] offset:36864
	ds_write_b128 v138, v[104:107] offset:40960
	ds_write_b128 v138, v[108:111] offset:45056
	s_waitcnt lgkmcnt(0)
	s_barrier
	global_load_dwordx4 v[96:99], v230, s[24:25] offset:640
	global_load_dwordx4 v[100:103], v230, s[30:31] offset:640
	global_load_dwordx4 v[104:107], v230, s[50:51] offset:640
	global_load_dwordx4 v[108:111], v230, s[54:55] offset:640
	ds_read_b128 v[142:145], v128 offset:32768
	ds_read_b128 v[146:149], v132 offset:49152
	ds_read_b128 v[150:153], v132 offset:53248
	ds_read_b128 v[154:157], v128 offset:36864
	s_waitcnt lgkmcnt(2)
	v_mfma_f32_32x32x16_bf16 v[48:63], v[142:145], v[146:149], v[48:63]
	s_waitcnt lgkmcnt(1)
	v_mfma_f32_32x32x16_bf16 v[32:47], v[142:145], v[150:153], v[32:47]
	s_waitcnt lgkmcnt(0)
	v_mfma_f32_32x32x16_bf16 v[16:31], v[154:157], v[146:149], v[16:31]
	ds_read_b128 v[146:149], v133 offset:49152
	v_mfma_f32_32x32x16_bf16 v[0:15], v[154:157], v[150:153], v[0:15]
	ds_read_b128 v[142:145], v129 offset:32768
	ds_read_b128 v[150:153], v133 offset:53248
	ds_read_b128 v[154:157], v129 offset:36864
	s_waitcnt lgkmcnt(2)
	v_mfma_f32_32x32x16_bf16 v[48:63], v[142:145], v[146:149], v[48:63]
	s_waitcnt lgkmcnt(1)
	v_mfma_f32_32x32x16_bf16 v[32:47], v[142:145], v[150:153], v[32:47]
	s_waitcnt lgkmcnt(0)
	v_mfma_f32_32x32x16_bf16 v[16:31], v[154:157], v[146:149], v[16:31]
	ds_read_b128 v[146:149], v228 offset:49152
	v_mfma_f32_32x32x16_bf16 v[0:15], v[154:157], v[150:153], v[0:15]
	ds_read_b128 v[142:145], v130 offset:32768
	ds_read_b128 v[150:153], v228 offset:53248
	ds_read_b128 v[154:157], v130 offset:36864
	s_waitcnt lgkmcnt(2)
	v_mfma_f32_32x32x16_bf16 v[48:63], v[142:145], v[146:149], v[48:63]
	s_waitcnt lgkmcnt(1)
	v_mfma_f32_32x32x16_bf16 v[32:47], v[142:145], v[150:153], v[32:47]
	s_waitcnt lgkmcnt(0)
	v_mfma_f32_32x32x16_bf16 v[16:31], v[154:157], v[146:149], v[16:31]
	ds_read_b128 v[146:149], v229 offset:49152
	v_mfma_f32_32x32x16_bf16 v[0:15], v[154:157], v[150:153], v[0:15]
	ds_read_b128 v[142:145], v131 offset:32768
	ds_read_b128 v[150:153], v229 offset:53248
	ds_read_b128 v[154:157], v131 offset:36864
	s_waitcnt lgkmcnt(2)
	v_mfma_f32_32x32x16_bf16 v[48:63], v[142:145], v[146:149], v[48:63]
	s_waitcnt lgkmcnt(1)
	v_mfma_f32_32x32x16_bf16 v[32:47], v[142:145], v[150:153], v[32:47]
	s_waitcnt lgkmcnt(0)
	v_mfma_f32_32x32x16_bf16 v[16:31], v[154:157], v[146:149], v[16:31]
	v_mfma_f32_32x32x16_bf16 v[0:15], v[154:157], v[150:153], v[0:15]
	s_waitcnt vmcnt(12)
	ds_write_b128 v138, v[160:163]
	ds_write_b128 v138, v[164:167] offset:4096
	ds_write_b128 v138, v[168:171] offset:8192
	ds_write_b128 v138, v[172:175] offset:12288
	s_waitcnt lgkmcnt(0)
	s_barrier
	global_load_dwordx4 v[160:163], v230, s[24:25] offset:768
	global_load_dwordx4 v[164:167], v230, s[30:31] offset:768
	global_load_dwordx4 v[168:171], v230, s[50:51] offset:768
	global_load_dwordx4 v[172:175], v230, s[54:55] offset:768
	ds_read_b128 v[142:145], v128
	ds_read_b128 v[146:149], v132 offset:16384
	ds_read_b128 v[150:153], v132 offset:20480
	ds_read_b128 v[154:157], v128 offset:4096
	s_waitcnt lgkmcnt(2)
	v_mfma_f32_32x32x16_bf16 v[48:63], v[142:145], v[146:149], v[48:63]
	s_waitcnt lgkmcnt(1)
	v_mfma_f32_32x32x16_bf16 v[32:47], v[142:145], v[150:153], v[32:47]
	s_waitcnt lgkmcnt(0)
	v_mfma_f32_32x32x16_bf16 v[16:31], v[154:157], v[146:149], v[16:31]
	ds_read_b128 v[146:149], v133 offset:16384
	v_mfma_f32_32x32x16_bf16 v[0:15], v[154:157], v[150:153], v[0:15]
	ds_read_b128 v[142:145], v129
	ds_read_b128 v[150:153], v133 offset:20480
	ds_read_b128 v[154:157], v129 offset:4096
	s_waitcnt lgkmcnt(2)
	v_mfma_f32_32x32x16_bf16 v[48:63], v[142:145], v[146:149], v[48:63]
	s_waitcnt lgkmcnt(1)
	v_mfma_f32_32x32x16_bf16 v[32:47], v[142:145], v[150:153], v[32:47]
	s_waitcnt lgkmcnt(0)
	v_mfma_f32_32x32x16_bf16 v[16:31], v[154:157], v[146:149], v[16:31]
	ds_read_b128 v[146:149], v228 offset:16384
	v_mfma_f32_32x32x16_bf16 v[0:15], v[154:157], v[150:153], v[0:15]
	ds_read_b128 v[142:145], v130
	ds_read_b128 v[150:153], v228 offset:20480
	ds_read_b128 v[154:157], v130 offset:4096
	s_waitcnt lgkmcnt(2)
	v_mfma_f32_32x32x16_bf16 v[48:63], v[142:145], v[146:149], v[48:63]
	s_waitcnt lgkmcnt(1)
	v_mfma_f32_32x32x16_bf16 v[32:47], v[142:145], v[150:153], v[32:47]
	s_waitcnt lgkmcnt(0)
	v_mfma_f32_32x32x16_bf16 v[16:31], v[154:157], v[146:149], v[16:31]
	ds_read_b128 v[146:149], v229 offset:16384
	v_mfma_f32_32x32x16_bf16 v[0:15], v[154:157], v[150:153], v[0:15]
	ds_read_b128 v[142:145], v131
	ds_read_b128 v[150:153], v229 offset:20480
	ds_read_b128 v[154:157], v131 offset:4096
	s_waitcnt lgkmcnt(2)
	v_mfma_f32_32x32x16_bf16 v[48:63], v[142:145], v[146:149], v[48:63]
	s_waitcnt lgkmcnt(1)
	v_mfma_f32_32x32x16_bf16 v[32:47], v[142:145], v[150:153], v[32:47]
	s_waitcnt lgkmcnt(0)
	v_mfma_f32_32x32x16_bf16 v[16:31], v[154:157], v[146:149], v[16:31]
	v_mfma_f32_32x32x16_bf16 v[0:15], v[154:157], v[150:153], v[0:15]
	s_waitcnt vmcnt(12)
	ds_write_b128 v138, v[196:199] offset:32768
	ds_write_b128 v138, v[200:203] offset:36864
	ds_write_b128 v138, v[204:207] offset:40960
	ds_write_b128 v138, v[208:211] offset:45056
	s_waitcnt lgkmcnt(0)
	s_barrier
	global_load_dwordx4 v[196:199], v230, s[24:25] offset:896
	global_load_dwordx4 v[200:203], v230, s[30:31] offset:896
	global_load_dwordx4 v[204:207], v230, s[50:51] offset:896
	global_load_dwordx4 v[208:211], v230, s[54:55] offset:896
	ds_read_b128 v[142:145], v128 offset:32768
	ds_read_b128 v[146:149], v132 offset:49152
	ds_read_b128 v[150:153], v132 offset:53248
	ds_read_b128 v[154:157], v128 offset:36864
	s_waitcnt lgkmcnt(2)
	v_mfma_f32_32x32x16_bf16 v[48:63], v[142:145], v[146:149], v[48:63]
	s_waitcnt lgkmcnt(1)
	v_mfma_f32_32x32x16_bf16 v[32:47], v[142:145], v[150:153], v[32:47]
	s_waitcnt lgkmcnt(0)
	v_mfma_f32_32x32x16_bf16 v[16:31], v[154:157], v[146:149], v[16:31]
	ds_read_b128 v[146:149], v133 offset:49152
	v_mfma_f32_32x32x16_bf16 v[0:15], v[154:157], v[150:153], v[0:15]
	ds_read_b128 v[142:145], v129 offset:32768
	ds_read_b128 v[150:153], v133 offset:53248
	ds_read_b128 v[154:157], v129 offset:36864
	s_waitcnt lgkmcnt(2)
	v_mfma_f32_32x32x16_bf16 v[48:63], v[142:145], v[146:149], v[48:63]
	s_waitcnt lgkmcnt(1)
	v_mfma_f32_32x32x16_bf16 v[32:47], v[142:145], v[150:153], v[32:47]
	s_waitcnt lgkmcnt(0)
	v_mfma_f32_32x32x16_bf16 v[16:31], v[154:157], v[146:149], v[16:31]
	ds_read_b128 v[146:149], v228 offset:49152
	v_mfma_f32_32x32x16_bf16 v[0:15], v[154:157], v[150:153], v[0:15]
	ds_read_b128 v[142:145], v130 offset:32768
	ds_read_b128 v[150:153], v228 offset:53248
	ds_read_b128 v[154:157], v130 offset:36864
	s_waitcnt lgkmcnt(2)
	v_mfma_f32_32x32x16_bf16 v[48:63], v[142:145], v[146:149], v[48:63]
	s_waitcnt lgkmcnt(1)
	v_mfma_f32_32x32x16_bf16 v[32:47], v[142:145], v[150:153], v[32:47]
	s_waitcnt lgkmcnt(0)
	v_mfma_f32_32x32x16_bf16 v[16:31], v[154:157], v[146:149], v[16:31]
	ds_read_b128 v[146:149], v229 offset:49152
	v_mfma_f32_32x32x16_bf16 v[0:15], v[154:157], v[150:153], v[0:15]
	ds_read_b128 v[142:145], v131 offset:32768
	ds_read_b128 v[150:153], v229 offset:53248
	ds_read_b128 v[154:157], v131 offset:36864
	s_waitcnt lgkmcnt(2)
	v_mfma_f32_32x32x16_bf16 v[48:63], v[142:145], v[146:149], v[48:63]
	s_waitcnt lgkmcnt(1)
	v_mfma_f32_32x32x16_bf16 v[32:47], v[142:145], v[150:153], v[32:47]
	s_waitcnt lgkmcnt(0)
	v_mfma_f32_32x32x16_bf16 v[16:31], v[154:157], v[146:149], v[16:31]
	v_mfma_f32_32x32x16_bf16 v[0:15], v[154:157], v[150:153], v[0:15]
	s_waitcnt vmcnt(12)
	ds_write_b128 v138, v[64:67]
	ds_write_b128 v138, v[68:71] offset:4096
	ds_write_b128 v138, v[72:75] offset:8192
	ds_write_b128 v138, v[76:79] offset:12288
	s_waitcnt lgkmcnt(0)
	s_barrier
	ds_read_b128 v[142:145], v128
	ds_read_b128 v[146:149], v132 offset:16384
	ds_read_b128 v[150:153], v132 offset:20480
	ds_read_b128 v[154:157], v128 offset:4096
	s_waitcnt lgkmcnt(2)
	v_mfma_f32_32x32x16_bf16 v[48:63], v[142:145], v[146:149], v[48:63]
	s_waitcnt lgkmcnt(1)
	v_mfma_f32_32x32x16_bf16 v[32:47], v[142:145], v[150:153], v[32:47]
	s_waitcnt lgkmcnt(0)
	v_mfma_f32_32x32x16_bf16 v[16:31], v[154:157], v[146:149], v[16:31]
	ds_read_b128 v[146:149], v133 offset:16384
	v_mfma_f32_32x32x16_bf16 v[0:15], v[154:157], v[150:153], v[0:15]
	ds_read_b128 v[142:145], v129
	ds_read_b128 v[150:153], v133 offset:20480
	ds_read_b128 v[154:157], v129 offset:4096
	s_waitcnt lgkmcnt(2)
	v_mfma_f32_32x32x16_bf16 v[48:63], v[142:145], v[146:149], v[48:63]
	s_waitcnt lgkmcnt(1)
	v_mfma_f32_32x32x16_bf16 v[32:47], v[142:145], v[150:153], v[32:47]
	s_waitcnt lgkmcnt(0)
	v_mfma_f32_32x32x16_bf16 v[16:31], v[154:157], v[146:149], v[16:31]
	ds_read_b128 v[146:149], v228 offset:16384
	v_mfma_f32_32x32x16_bf16 v[0:15], v[154:157], v[150:153], v[0:15]
	ds_read_b128 v[142:145], v130
	ds_read_b128 v[150:153], v228 offset:20480
	ds_read_b128 v[154:157], v130 offset:4096
	s_waitcnt lgkmcnt(2)
	v_mfma_f32_32x32x16_bf16 v[48:63], v[142:145], v[146:149], v[48:63]
	s_waitcnt lgkmcnt(1)
	v_mfma_f32_32x32x16_bf16 v[32:47], v[142:145], v[150:153], v[32:47]
	s_waitcnt lgkmcnt(0)
	v_mfma_f32_32x32x16_bf16 v[16:31], v[154:157], v[146:149], v[16:31]
	ds_read_b128 v[146:149], v229 offset:16384
	v_mfma_f32_32x32x16_bf16 v[0:15], v[154:157], v[150:153], v[0:15]
	ds_read_b128 v[142:145], v131
	ds_read_b128 v[150:153], v229 offset:20480
	ds_read_b128 v[154:157], v131 offset:4096
	s_waitcnt lgkmcnt(2)
	v_mfma_f32_32x32x16_bf16 v[48:63], v[142:145], v[146:149], v[48:63]
	s_waitcnt lgkmcnt(1)
	v_mfma_f32_32x32x16_bf16 v[32:47], v[142:145], v[150:153], v[32:47]
	s_waitcnt lgkmcnt(0)
	v_mfma_f32_32x32x16_bf16 v[16:31], v[154:157], v[146:149], v[16:31]
	v_mfma_f32_32x32x16_bf16 v[0:15], v[154:157], v[150:153], v[0:15]
	s_waitcnt vmcnt(8)
	ds_write_b128 v138, v[96:99] offset:32768
	ds_write_b128 v138, v[100:103] offset:36864
	ds_write_b128 v138, v[104:107] offset:40960
	ds_write_b128 v138, v[108:111] offset:45056
	s_waitcnt lgkmcnt(0)
	s_barrier
	ds_read_b128 v[142:145], v128 offset:32768
	ds_read_b128 v[146:149], v132 offset:49152
	ds_read_b128 v[150:153], v132 offset:53248
	ds_read_b128 v[154:157], v128 offset:36864
	s_waitcnt lgkmcnt(2)
	v_mfma_f32_32x32x16_bf16 v[48:63], v[142:145], v[146:149], v[48:63]
	s_waitcnt lgkmcnt(1)
	v_mfma_f32_32x32x16_bf16 v[32:47], v[142:145], v[150:153], v[32:47]
	s_waitcnt lgkmcnt(0)
	v_mfma_f32_32x32x16_bf16 v[16:31], v[154:157], v[146:149], v[16:31]
	ds_read_b128 v[146:149], v133 offset:49152
	v_mfma_f32_32x32x16_bf16 v[0:15], v[154:157], v[150:153], v[0:15]
	ds_read_b128 v[142:145], v129 offset:32768
	ds_read_b128 v[150:153], v133 offset:53248
	ds_read_b128 v[154:157], v129 offset:36864
	s_waitcnt lgkmcnt(2)
	v_mfma_f32_32x32x16_bf16 v[48:63], v[142:145], v[146:149], v[48:63]
	s_waitcnt lgkmcnt(1)
	v_mfma_f32_32x32x16_bf16 v[32:47], v[142:145], v[150:153], v[32:47]
	s_waitcnt lgkmcnt(0)
	v_mfma_f32_32x32x16_bf16 v[16:31], v[154:157], v[146:149], v[16:31]
	ds_read_b128 v[146:149], v228 offset:49152
	v_mfma_f32_32x32x16_bf16 v[0:15], v[154:157], v[150:153], v[0:15]
	ds_read_b128 v[142:145], v130 offset:32768
	ds_read_b128 v[150:153], v228 offset:53248
	ds_read_b128 v[154:157], v130 offset:36864
	s_waitcnt lgkmcnt(2)
	v_mfma_f32_32x32x16_bf16 v[48:63], v[142:145], v[146:149], v[48:63]
	s_waitcnt lgkmcnt(1)
	v_mfma_f32_32x32x16_bf16 v[32:47], v[142:145], v[150:153], v[32:47]
	s_waitcnt lgkmcnt(0)
	v_mfma_f32_32x32x16_bf16 v[16:31], v[154:157], v[146:149], v[16:31]
	ds_read_b128 v[146:149], v229 offset:49152
	v_mfma_f32_32x32x16_bf16 v[0:15], v[154:157], v[150:153], v[0:15]
	ds_read_b128 v[142:145], v131 offset:32768
	ds_read_b128 v[150:153], v229 offset:53248
	ds_read_b128 v[154:157], v131 offset:36864
	s_waitcnt lgkmcnt(2)
	v_mfma_f32_32x32x16_bf16 v[48:63], v[142:145], v[146:149], v[48:63]
	s_waitcnt lgkmcnt(1)
	v_mfma_f32_32x32x16_bf16 v[32:47], v[142:145], v[150:153], v[32:47]
	s_waitcnt lgkmcnt(0)
	v_mfma_f32_32x32x16_bf16 v[16:31], v[154:157], v[146:149], v[16:31]
	v_mfma_f32_32x32x16_bf16 v[0:15], v[154:157], v[150:153], v[0:15]
	s_waitcnt vmcnt(4)
	ds_write_b128 v138, v[160:163]
	ds_write_b128 v138, v[164:167] offset:4096
	ds_write_b128 v138, v[168:171] offset:8192
	ds_write_b128 v138, v[172:175] offset:12288
	s_waitcnt lgkmcnt(0)
	s_barrier
	ds_read_b128 v[142:145], v128
	ds_read_b128 v[146:149], v132 offset:16384
	ds_read_b128 v[150:153], v132 offset:20480
	ds_read_b128 v[154:157], v128 offset:4096
	s_waitcnt lgkmcnt(2)
	v_mfma_f32_32x32x16_bf16 v[48:63], v[142:145], v[146:149], v[48:63]
	s_waitcnt lgkmcnt(1)
	v_mfma_f32_32x32x16_bf16 v[32:47], v[142:145], v[150:153], v[32:47]
	s_waitcnt lgkmcnt(0)
	v_mfma_f32_32x32x16_bf16 v[16:31], v[154:157], v[146:149], v[16:31]
	ds_read_b128 v[146:149], v133 offset:16384
	v_mfma_f32_32x32x16_bf16 v[0:15], v[154:157], v[150:153], v[0:15]
	ds_read_b128 v[142:145], v129
	ds_read_b128 v[150:153], v133 offset:20480
	ds_read_b128 v[154:157], v129 offset:4096
	s_waitcnt lgkmcnt(2)
	v_mfma_f32_32x32x16_bf16 v[48:63], v[142:145], v[146:149], v[48:63]
	s_waitcnt lgkmcnt(1)
	v_mfma_f32_32x32x16_bf16 v[32:47], v[142:145], v[150:153], v[32:47]
	s_waitcnt lgkmcnt(0)
	v_mfma_f32_32x32x16_bf16 v[16:31], v[154:157], v[146:149], v[16:31]
	ds_read_b128 v[146:149], v228 offset:16384
	v_mfma_f32_32x32x16_bf16 v[0:15], v[154:157], v[150:153], v[0:15]
	ds_read_b128 v[142:145], v130
	ds_read_b128 v[150:153], v228 offset:20480
	ds_read_b128 v[154:157], v130 offset:4096
	s_waitcnt lgkmcnt(2)
	v_mfma_f32_32x32x16_bf16 v[48:63], v[142:145], v[146:149], v[48:63]
	s_waitcnt lgkmcnt(1)
	v_mfma_f32_32x32x16_bf16 v[32:47], v[142:145], v[150:153], v[32:47]
	s_waitcnt lgkmcnt(0)
	v_mfma_f32_32x32x16_bf16 v[16:31], v[154:157], v[146:149], v[16:31]
	ds_read_b128 v[146:149], v229 offset:16384
	v_mfma_f32_32x32x16_bf16 v[0:15], v[154:157], v[150:153], v[0:15]
	ds_read_b128 v[142:145], v131
	ds_read_b128 v[150:153], v229 offset:20480
	ds_read_b128 v[154:157], v131 offset:4096
	s_waitcnt lgkmcnt(2)
	v_mfma_f32_32x32x16_bf16 v[48:63], v[142:145], v[146:149], v[48:63]
	s_waitcnt lgkmcnt(1)
	v_mfma_f32_32x32x16_bf16 v[32:47], v[142:145], v[150:153], v[32:47]
	s_waitcnt lgkmcnt(0)
	v_mfma_f32_32x32x16_bf16 v[16:31], v[154:157], v[146:149], v[16:31]
	v_mfma_f32_32x32x16_bf16 v[0:15], v[154:157], v[150:153], v[0:15]
	s_waitcnt vmcnt(0)
	ds_write_b128 v138, v[196:199] offset:32768
	ds_write_b128 v138, v[200:203] offset:36864
	ds_write_b128 v138, v[204:207] offset:40960
	ds_write_b128 v138, v[208:211] offset:45056
	s_waitcnt lgkmcnt(0)
	s_barrier
	ds_read_b128 v[142:145], v128 offset:32768
	ds_read_b128 v[146:149], v132 offset:49152
	ds_read_b128 v[150:153], v132 offset:53248
	ds_read_b128 v[154:157], v128 offset:36864
	s_waitcnt lgkmcnt(2)
	v_mfma_f32_32x32x16_bf16 v[48:63], v[142:145], v[146:149], v[48:63]
	s_waitcnt lgkmcnt(1)
	v_mfma_f32_32x32x16_bf16 v[32:47], v[142:145], v[150:153], v[32:47]
	s_waitcnt lgkmcnt(0)
	v_mfma_f32_32x32x16_bf16 v[16:31], v[154:157], v[146:149], v[16:31]
	ds_read_b128 v[146:149], v133 offset:49152
	v_mfma_f32_32x32x16_bf16 v[0:15], v[154:157], v[150:153], v[0:15]
	ds_read_b128 v[142:145], v129 offset:32768
	ds_read_b128 v[150:153], v133 offset:53248
	ds_read_b128 v[154:157], v129 offset:36864
	s_waitcnt lgkmcnt(2)
	v_mfma_f32_32x32x16_bf16 v[48:63], v[142:145], v[146:149], v[48:63]
	s_waitcnt lgkmcnt(1)
	v_mfma_f32_32x32x16_bf16 v[32:47], v[142:145], v[150:153], v[32:47]
	s_waitcnt lgkmcnt(0)
	v_mfma_f32_32x32x16_bf16 v[16:31], v[154:157], v[146:149], v[16:31]
	ds_read_b128 v[146:149], v228 offset:49152
	v_mfma_f32_32x32x16_bf16 v[0:15], v[154:157], v[150:153], v[0:15]
	ds_read_b128 v[142:145], v130 offset:32768
	ds_read_b128 v[150:153], v228 offset:53248
	ds_read_b128 v[154:157], v130 offset:36864
	s_waitcnt lgkmcnt(2)
	v_mfma_f32_32x32x16_bf16 v[48:63], v[142:145], v[146:149], v[48:63]
	s_waitcnt lgkmcnt(1)
	v_mfma_f32_32x32x16_bf16 v[32:47], v[142:145], v[150:153], v[32:47]
	s_waitcnt lgkmcnt(0)
	v_mfma_f32_32x32x16_bf16 v[16:31], v[154:157], v[146:149], v[16:31]
	ds_read_b128 v[146:149], v229 offset:49152
	v_mfma_f32_32x32x16_bf16 v[0:15], v[154:157], v[150:153], v[0:15]
	ds_read_b128 v[142:145], v131 offset:32768
	ds_read_b128 v[150:153], v229 offset:53248
	ds_read_b128 v[154:157], v131 offset:36864
	s_waitcnt lgkmcnt(2)
	v_mfma_f32_32x32x16_bf16 v[48:63], v[142:145], v[146:149], v[48:63]
	s_waitcnt lgkmcnt(1)
	v_mfma_f32_32x32x16_bf16 v[32:47], v[142:145], v[150:153], v[32:47]
	s_waitcnt lgkmcnt(0)
	v_mfma_f32_32x32x16_bf16 v[16:31], v[154:157], v[146:149], v[16:31]
	v_mfma_f32_32x32x16_bf16 v[0:15], v[154:157], v[150:153], v[0:15]
	s_barrier
